# SSM output GEMM epilogue: the 16 serial u-tile reads are issued up front (counted waits, register copies)
# baseline (speedup 1.0000x reference)
.LBB0_485:
	s_lshl_b32 s2, s18, 4
	s_ashr_i32 s3, s2, 31
	v_ashrrev_i32_e32 v138, 2, v144
	s_lshl_b64 s[4:5], s[2:3], 2
	v_lshrrev_b32_e32 v0, 1, v144
	v_and_b32_e32 v138, 0xffffffc0, v138
	s_add_u32 s4, s28, s4
	v_and_b32_e32 v147, 8, v0
	v_add_u32_e32 v138, s8, v138
	s_addc_u32 s5, s58, s5
	v_lshlrev_b32_e32 v38, 2, v147
	v_and_or_b32 v142, v144, 15, v138
	s_barrier
	global_load_dwordx4 v[26:29], v38, s[4:5] offset:16
	s_nop 0
	global_load_dwordx4 v[38:41], v38, s[4:5]
	v_and_b32_e32 v146, 0x78, v0
	v_ashrrev_i32_e32 v143, 31, v142
	v_lshlrev_b64 v[138:139], 9, v[142:143]
	v_lshl_add_u64 v[138:139], s[0:1], 0, v[138:139]
	v_lshlrev_b32_e32 v0, 1, v146
	v_lshl_add_u64 v[144:145], v[138:139], 0, v[0:1]
	global_load_dwordx4 v[138:141], v[144:145], off
	v_lshl_add_u32 v194, v142, 9, v0
	global_load_dwordx4 v[160:163], v194, s[0:1] offset:256
	v_add_u32_e32 v195, 0x2000, v194
	global_load_dwordx4 v[176:179], v195, s[0:1]
	global_load_dwordx4 v[196:199], v195, s[0:1] offset:256
	v_add_u32_e32 v195, 0x4000, v194
	global_load_dwordx4 v[200:203], v195, s[0:1]
	global_load_dwordx4 v[204:207], v195, s[0:1] offset:256
	v_add_u32_e32 v195, 0x6000, v194
	global_load_dwordx4 v[208:211], v195, s[0:1]
	global_load_dwordx4 v[212:215], v195, s[0:1] offset:256
	v_add_u32_e32 v195, 0x10000, v194
	global_load_dwordx4 v[216:219], v195, s[0:1]
	global_load_dwordx4 v[220:223], v195, s[0:1] offset:256
	v_add_u32_e32 v195, 0x12000, v194
	global_load_dwordx4 v[224:227], v195, s[0:1]
	global_load_dwordx4 v[228:231], v195, s[0:1] offset:256
	v_add_u32_e32 v195, 0x14000, v194
	global_load_dwordx4 v[232:235], v195, s[0:1]
	global_load_dwordx4 v[236:239], v195, s[0:1] offset:256
	v_add_u32_e32 v195, 0x16000, v194
	global_load_dwordx4 v[240:243], v195, s[0:1]
	s_mov_b32 s11, 0x3f200000
	s_waitcnt vmcnt(14)
	v_lshlrev_b32_e32 v143, 16, v138
	v_fma_f32 v134, v38, v143, v134
	v_mul_f32_e32 v143, 0x3d372713, v134
	v_mul_f32_e32 v143, v134, v143
	v_fma_f32 v143, v134, v143, v134
	v_mul_f32_e32 v143, 0x3f4c422a, v143
	s_mov_b32 s70, 0x800000
	s_mov_b32 s50, 0x8000
	s_movk_i32 s55, 0xff
	s_mov_b32 s51, 0x40000
	s_movk_i32 s48, 0x1200
	s_movk_i32 s49, 0x3000
	s_movk_i32 s56, 0x4000
	s_mov_b32 s57, 0x27fff
	s_movk_i32 s65, 0x400
	s_brev_b32 s10, -2
	s_mov_b64 s[52:53], 0x800
	v_mul_f32_e64 v148, |v143|, s76
	v_add_f32_e32 v148, v148, v148
	v_exp_f32_e32 v148, v148
	s_nop 0
	v_add_f32_e32 v148, 1.0, v148
	v_rcp_f32_e32 v148, v148
	s_nop 0
	v_fma_f32 v148, v148, -2.0, 1.0
	v_lshlrev_b32_e32 v149, 16, v140
	v_fma_f32 v130, v26, v149, v130
	v_mul_f32_e32 v149, 0x3d372713, v130
	v_mul_f32_e32 v149, v130, v149
	v_fma_f32 v149, v130, v149, v130
	v_mul_f32_e32 v149, 0x3f4c422a, v149
	v_mul_f32_e64 v150, |v149|, s76
	v_add_f32_e32 v150, v150, v150
	v_exp_f32_e32 v150, v150
	s_nop 0
	v_add_f32_e32 v150, 1.0, v150
	v_rcp_f32_e32 v150, v150
	s_nop 0
	v_fma_f32 v150, v150, -2.0, 1.0
	v_and_b32_e32 v138, 0xffff0000, v138
	v_fma_f32 v138, v39, v138, v135
	v_mul_f32_e32 v135, 0x3d372713, v138
	v_mul_f32_e32 v135, v138, v135
	v_fma_f32 v135, v138, v135, v138
	v_mul_f32_e32 v135, 0x3f4c422a, v135
	v_mul_f32_e64 v151, |v135|, s76
	v_add_f32_e32 v151, v151, v151
	v_exp_f32_e32 v151, v151
	s_nop 0
	v_add_f32_e32 v151, 1.0, v151
	v_rcp_f32_e32 v151, v151
	s_nop 0
	v_fma_f32 v151, v151, -2.0, 1.0
	v_and_b32_e32 v140, 0xffff0000, v140
	v_fma_f32 v140, v27, v140, v131
	v_mul_f32_e32 v131, 0x3d372713, v140
	v_mul_f32_e32 v131, v140, v131
	v_fma_f32 v131, v140, v131, v140
	v_mul_f32_e32 v131, 0x3f4c422a, v131
	v_mul_f32_e64 v152, |v131|, s76
	v_add_f32_e32 v152, v152, v152
	v_exp_f32_e32 v152, v152
	s_nop 0
	v_add_f32_e32 v152, 1.0, v152
	v_rcp_f32_e32 v152, v152
	s_nop 0
	v_fma_f32 v152, v152, -2.0, 1.0
	v_lshlrev_b32_e32 v153, 16, v139
	v_fma_f32 v136, v40, v153, v136
	v_mul_f32_e32 v153, 0x3d372713, v136
	v_mul_f32_e32 v153, v136, v153
	v_fma_f32 v153, v136, v153, v136
	v_mul_f32_e32 v153, 0x3f4c422a, v153
	v_mul_f32_e64 v154, |v153|, s76
	v_add_f32_e32 v154, v154, v154
	v_exp_f32_e32 v154, v154
	s_nop 0
	v_add_f32_e32 v154, 1.0, v154
	v_rcp_f32_e32 v154, v154
	s_nop 0
	v_fma_f32 v154, v154, -2.0, 1.0
	v_lshlrev_b32_e32 v155, 16, v141
	v_fma_f32 v132, v28, v155, v132
	v_mul_f32_e32 v155, 0x3d372713, v132
	v_mul_f32_e32 v155, v132, v155
	v_fma_f32 v155, v132, v155, v132
	v_mul_f32_e32 v155, 0x3f4c422a, v155
	v_mul_f32_e64 v157, |v155|, s76
	v_add_f32_e32 v157, v157, v157
	v_exp_f32_e32 v157, v157
	s_nop 0
	v_add_f32_e32 v157, 1.0, v157
	v_rcp_f32_e32 v157, v157
	s_nop 0
	v_fma_f32 v157, v157, -2.0, 1.0
	v_and_b32_e32 v139, 0xffff0000, v139
	v_fmac_f32_e32 v137, v41, v139
	v_mul_f32_e32 v139, 0x3d372713, v137
	v_mul_f32_e32 v139, v137, v139
	v_fma_f32 v139, v137, v139, v137
	v_mul_f32_e32 v139, 0x3f4c422a, v139
	v_mul_f32_e64 v158, |v139|, s76
	v_add_f32_e32 v158, v158, v158
	v_exp_f32_e32 v158, v158
	s_nop 0
	v_add_f32_e32 v158, 1.0, v158
	v_rcp_f32_e32 v158, v158
	s_nop 0
	v_fma_f32 v158, v158, -2.0, 1.0
	v_and_b32_e32 v141, 0xffff0000, v141
	v_fmac_f32_e32 v133, v29, v141
	v_mul_f32_e32 v141, 0x3d372713, v133
	v_mul_f32_e32 v141, v133, v141
	v_fma_f32 v141, v133, v141, v133
	v_mul_f32_e32 v141, 0x3f4c422a, v141
	v_mul_f32_e64 v159, |v141|, s76
	v_add_f32_e32 v159, v159, v159
	v_exp_f32_e32 v159, v159
	s_nop 0
	v_add_f32_e32 v159, 1.0, v159
	v_rcp_f32_e32 v159, v159
	s_nop 0
	v_fma_f32 v159, v159, -2.0, 1.0
	v_bfi_b32 v153, s10, v154, v153
	v_mul_f32_e32 v136, 0.5, v136
	v_add_f32_e32 v153, 1.0, v153
	v_mul_f32_e32 v153, v136, v153
	v_bfi_b32 v136, s10, v158, v139
	v_mul_f32_e32 v137, 0.5, v137
	v_add_f32_e32 v136, 1.0, v136
	v_mul_f32_e32 v154, v137, v136
	v_bfi_b32 v136, s10, v157, v155
	v_mul_f32_e32 v132, 0.5, v132
	v_add_f32_e32 v136, 1.0, v136
	v_mul_f32_e32 v155, v132, v136
	v_bfi_b32 v136, s10, v150, v149
	v_mul_f32_e32 v130, 0.5, v130
	v_add_f32_e32 v136, 1.0, v136
	v_mul_f32_e32 v132, 0.5, v140
	v_mul_f32_e32 v140, v130, v136
	v_bfi_b32 v130, s10, v152, v131
	v_mul_f32_e32 v131, 0.5, v134
	v_bfi_b32 v134, s10, v148, v143
	v_add_f32_e32 v134, 1.0, v134
	v_add_f32_e32 v130, 1.0, v130
	v_mul_f32_e32 v143, v131, v134
	v_bfi_b32 v131, s10, v151, v135
	s_lshl_b64 s[2:3], s[2:3], 1
	v_mul_f32_e32 v132, v132, v130
	v_mul_f32_e32 v130, 0.5, v138
	v_add_f32_e32 v131, 1.0, v131
	s_add_u32 s2, s90, s2
	v_mul_f32_e32 v148, v130, v131
	s_addc_u32 s3, s91, s3
	v_lshlrev_b32_e32 v130, 1, v147
	v_mov_b32_e32 v131, v1
	v_lshl_add_u64 v[134:135], s[2:3], 0, v[130:131]
	v_bfi_b32 v130, s10, v159, v141
	v_mul_f32_e32 v133, 0.5, v133
	v_lshlrev_b32_e32 v137, 4, v142
	v_add_f32_e32 v130, 1.0, v130
	v_lshrrev_b32_e32 v136, 4, v146
	v_mul_f32_e32 v133, v133, v130
	v_or_b32_e32 v130, v137, v136
	v_ashrrev_i32_e32 v131, 31, v130
	v_lshlrev_b64 v[130:131], 10, v[130:131]
	v_lshl_add_u64 v[138:139], v[134:135], 0, v[130:131]
	v_cvt_pk_bf16_f32 v130, v143, v148
	v_cvt_pk_bf16_f32 v131, v153, v154
	v_cvt_pk_bf16_f32 v132, v140, v132
	v_cvt_pk_bf16_f32 v133, v155, v133
	global_store_dwordx4 v[138:139], v[130:133], off
	s_nop 1
	v_mov_b64_e32 v[130:131], v[160:161]
	v_mov_b64_e32 v[132:133], v[162:163]
	s_waitcnt vmcnt(14)
	v_lshlrev_b32_e32 v138, 16, v130
	v_fma_f32 v126, v38, v138, v126
	v_mul_f32_e32 v138, 0x3d372713, v126
	v_mul_f32_e32 v138, v126, v138
	v_fma_f32 v138, v126, v138, v126
	v_mul_f32_e32 v138, 0x3f4c422a, v138
	v_mul_f32_e64 v139, |v138|, s76
	v_add_f32_e32 v139, v139, v139
	v_exp_f32_e32 v139, v139
	s_nop 0
	v_add_f32_e32 v139, 1.0, v139
	v_rcp_f32_e32 v139, v139
	s_nop 0
	v_fma_f32 v139, v139, -2.0, 1.0
	v_lshlrev_b32_e32 v140, 16, v132
	v_fma_f32 v122, v26, v140, v122
	v_mul_f32_e32 v140, 0x3d372713, v122
	v_mul_f32_e32 v140, v122, v140
	v_fma_f32 v140, v122, v140, v122
	v_mul_f32_e32 v140, 0x3f4c422a, v140
	v_mul_f32_e64 v141, |v140|, s76
	v_add_f32_e32 v141, v141, v141
	v_exp_f32_e32 v141, v141
	s_nop 0
	v_add_f32_e32 v141, 1.0, v141
	v_rcp_f32_e32 v141, v141
	s_nop 0
	v_fma_f32 v141, v141, -2.0, 1.0
	v_and_b32_e32 v130, 0xffff0000, v130
	v_fma_f32 v130, v39, v130, v127
	v_mul_f32_e32 v127, 0x3d372713, v130
	v_mul_f32_e32 v127, v130, v127
	v_fma_f32 v127, v130, v127, v130
	v_mul_f32_e32 v127, 0x3f4c422a, v127
	v_mul_f32_e64 v143, |v127|, s76
	v_add_f32_e32 v143, v143, v143
	v_exp_f32_e32 v143, v143
	s_nop 0
	v_add_f32_e32 v143, 1.0, v143
	v_rcp_f32_e32 v143, v143
	s_nop 0
	v_fma_f32 v143, v143, -2.0, 1.0
	v_and_b32_e32 v132, 0xffff0000, v132
	v_fma_f32 v132, v27, v132, v123
	v_mul_f32_e32 v123, 0x3d372713, v132
	v_mul_f32_e32 v123, v132, v123
	v_fma_f32 v123, v132, v123, v132
	v_mul_f32_e32 v123, 0x3f4c422a, v123
	v_mul_f32_e64 v144, |v123|, s76
	v_add_f32_e32 v144, v144, v144
	v_exp_f32_e32 v144, v144
	s_nop 0
	v_add_f32_e32 v144, 1.0, v144
	v_rcp_f32_e32 v144, v144
	s_nop 0
	v_fma_f32 v144, v144, -2.0, 1.0
	v_lshlrev_b32_e32 v145, 16, v131
	v_fma_f32 v128, v40, v145, v128
	v_mul_f32_e32 v145, 0x3d372713, v128
	v_mul_f32_e32 v145, v128, v145
	v_fma_f32 v145, v128, v145, v128
	v_mul_f32_e32 v145, 0x3f4c422a, v145
	v_mul_f32_e64 v147, |v145|, s76
	v_add_f32_e32 v147, v147, v147
	v_exp_f32_e32 v147, v147
	s_nop 0
	v_add_f32_e32 v147, 1.0, v147
	v_rcp_f32_e32 v147, v147
	s_nop 0
	v_fma_f32 v147, v147, -2.0, 1.0
	v_lshlrev_b32_e32 v148, 16, v133
	v_fma_f32 v124, v28, v148, v124
	v_mul_f32_e32 v148, 0x3d372713, v124
	v_mul_f32_e32 v148, v124, v148
	v_fma_f32 v148, v124, v148, v124
	v_mul_f32_e32 v148, 0x3f4c422a, v148
	v_mul_f32_e64 v149, |v148|, s76
	v_add_f32_e32 v149, v149, v149
	v_exp_f32_e32 v149, v149
	s_nop 0
	v_add_f32_e32 v149, 1.0, v149
	v_rcp_f32_e32 v149, v149
	s_nop 0
	v_fma_f32 v149, v149, -2.0, 1.0
	v_and_b32_e32 v131, 0xffff0000, v131
	v_fmac_f32_e32 v129, v41, v131
	v_mul_f32_e32 v131, 0x3d372713, v129
	v_mul_f32_e32 v131, v129, v131
	v_fma_f32 v131, v129, v131, v129
	v_mul_f32_e32 v131, 0x3f4c422a, v131
	v_mul_f32_e64 v150, |v131|, s76
	v_add_f32_e32 v150, v150, v150
	v_exp_f32_e32 v150, v150
	s_nop 0
	v_add_f32_e32 v150, 1.0, v150
	v_rcp_f32_e32 v150, v150
	s_nop 0
	v_fma_f32 v150, v150, -2.0, 1.0
	v_and_b32_e32 v133, 0xffff0000, v133
	v_fmac_f32_e32 v125, v29, v133
	v_mul_f32_e32 v133, 0x3d372713, v125
	v_mul_f32_e32 v133, v125, v133
	v_fma_f32 v133, v125, v133, v125
	v_mul_f32_e32 v133, 0x3f4c422a, v133
	v_mul_f32_e64 v151, |v133|, s76
	v_add_f32_e32 v151, v151, v151
	v_exp_f32_e32 v151, v151
	s_nop 0
	v_add_f32_e32 v151, 1.0, v151
	v_rcp_f32_e32 v151, v151
	s_nop 0
	v_fma_f32 v151, v151, -2.0, 1.0
	v_bfi_b32 v131, s10, v150, v131
	v_mul_f32_e32 v129, 0.5, v129
	v_add_f32_e32 v131, 1.0, v131
	v_mul_f32_e32 v129, v129, v131
	v_bfi_b32 v131, s10, v149, v148
	v_mul_f32_e32 v124, 0.5, v124
	v_add_f32_e32 v131, 1.0, v131
	v_mul_f32_e32 v131, v124, v131
	v_mul_f32_e32 v124, 0.5, v132
	v_bfi_b32 v132, s10, v141, v140
	v_mul_f32_e32 v122, 0.5, v122
	v_add_f32_e32 v132, 1.0, v132
	v_mul_f32_e32 v132, v122, v132
	v_bfi_b32 v122, s10, v144, v123
	v_mul_f32_e32 v123, 0.5, v126
	v_bfi_b32 v126, s10, v139, v138
	v_add_f32_e32 v126, 1.0, v126
	v_add_f32_e32 v122, 1.0, v122
	v_mul_f32_e32 v138, v123, v126
	v_bfi_b32 v123, s10, v143, v127
	v_mul_f32_e32 v124, v124, v122
	v_mul_f32_e32 v122, 0.5, v130
	v_add_f32_e32 v123, 1.0, v123
	v_mul_f32_e32 v139, v122, v123
	v_or_b32_e32 v122, 0x80, v146
	v_bfi_b32 v123, s10, v151, v133
	v_lshrrev_b32_e32 v130, 4, v122
	v_bfi_b32 v145, s10, v147, v145
	v_mul_f32_e32 v125, 0.5, v125
	v_add_f32_e32 v123, 1.0, v123
	v_or_b32_e32 v122, v137, v130
	v_mul_f32_e32 v128, 0.5, v128
	v_add_f32_e32 v145, 1.0, v145
	v_mul_f32_e32 v125, v125, v123
	v_ashrrev_i32_e32 v123, 31, v122
	v_mul_f32_e32 v128, v128, v145
	v_lshlrev_b64 v[122:123], 10, v[122:123]
	v_lshl_add_u64 v[126:127], v[134:135], 0, v[122:123]
	v_cvt_pk_bf16_f32 v123, v128, v129
	v_add_u32_e32 v128, 16, v142
	v_cvt_pk_bf16_f32 v122, v138, v139
	v_cvt_pk_bf16_f32 v124, v132, v124
	v_cvt_pk_bf16_f32 v125, v131, v125
	v_ashrrev_i32_e32 v129, 31, v128
	global_store_dwordx4 v[126:127], v[122:125], off
	s_nop 1
	v_lshlrev_b64 v[122:123], 9, v[128:129]
	v_lshl_add_u64 v[122:123], s[0:1], 0, v[122:123]
	v_lshl_add_u64 v[126:127], v[122:123], 0, v[0:1]
	s_nop 1
	v_mov_b64_e32 v[122:123], v[176:177]
	v_mov_b64_e32 v[124:125], v[178:179]
	s_waitcnt vmcnt(14)
	v_lshlrev_b32_e32 v129, 16, v122
	v_fma_f32 v118, v38, v129, v118
	v_mul_f32_e32 v129, 0x3d372713, v118
	v_mul_f32_e32 v129, v118, v129
	v_fma_f32 v129, v118, v129, v118
	v_mul_f32_e32 v129, 0x3f4c422a, v129
	v_mul_f32_e64 v131, |v129|, s76
	v_add_f32_e32 v131, v131, v131
	v_exp_f32_e32 v131, v131
	s_nop 0
	v_add_f32_e32 v131, 1.0, v131
	v_rcp_f32_e32 v131, v131
	s_nop 0
	v_fma_f32 v131, v131, -2.0, 1.0
	v_lshlrev_b32_e32 v132, 16, v124
	v_fma_f32 v114, v26, v132, v114
	v_mul_f32_e32 v132, 0x3d372713, v114
	v_mul_f32_e32 v132, v114, v132
	v_fma_f32 v132, v114, v132, v114
	v_mul_f32_e32 v132, 0x3f4c422a, v132
	v_mul_f32_e64 v133, |v132|, s76
	v_add_f32_e32 v133, v133, v133
	v_exp_f32_e32 v133, v133
	s_nop 0
	v_add_f32_e32 v133, 1.0, v133
	v_rcp_f32_e32 v133, v133
	s_nop 0
	v_fma_f32 v133, v133, -2.0, 1.0
	v_and_b32_e32 v122, 0xffff0000, v122
	v_fma_f32 v122, v39, v122, v119
	v_mul_f32_e32 v119, 0x3d372713, v122
	v_mul_f32_e32 v119, v122, v119
	v_fma_f32 v119, v122, v119, v122
	v_mul_f32_e32 v119, 0x3f4c422a, v119
	v_mul_f32_e64 v137, |v119|, s76
	v_add_f32_e32 v137, v137, v137
	v_exp_f32_e32 v137, v137
	s_nop 0
	v_add_f32_e32 v137, 1.0, v137
	v_rcp_f32_e32 v137, v137
	s_nop 0
	v_fma_f32 v137, v137, -2.0, 1.0
	v_and_b32_e32 v124, 0xffff0000, v124
	v_fma_f32 v124, v27, v124, v115
	v_mul_f32_e32 v115, 0x3d372713, v124
	v_mul_f32_e32 v115, v124, v115
	v_fma_f32 v115, v124, v115, v124
	v_mul_f32_e32 v115, 0x3f4c422a, v115
	v_mul_f32_e64 v138, |v115|, s76
	v_add_f32_e32 v138, v138, v138
	v_exp_f32_e32 v138, v138
	s_nop 0
	v_add_f32_e32 v138, 1.0, v138
	v_rcp_f32_e32 v138, v138
	s_nop 0
	v_fma_f32 v138, v138, -2.0, 1.0
	v_lshlrev_b32_e32 v139, 16, v123
	v_fma_f32 v120, v40, v139, v120
	v_mul_f32_e32 v139, 0x3d372713, v120
	v_mul_f32_e32 v139, v120, v139
	v_fma_f32 v139, v120, v139, v120
	v_mul_f32_e32 v139, 0x3f4c422a, v139
	v_mul_f32_e64 v140, |v139|, s76
	v_add_f32_e32 v140, v140, v140
	v_exp_f32_e32 v140, v140
	s_nop 0
	v_add_f32_e32 v140, 1.0, v140
	v_rcp_f32_e32 v140, v140
	s_nop 0
	v_fma_f32 v140, v140, -2.0, 1.0
	v_lshlrev_b32_e32 v141, 16, v125
	v_fma_f32 v116, v28, v141, v116
	v_mul_f32_e32 v141, 0x3d372713, v116
	v_mul_f32_e32 v141, v116, v141
	v_fma_f32 v141, v116, v141, v116
	v_mul_f32_e32 v141, 0x3f4c422a, v141
	v_mul_f32_e64 v143, |v141|, s76
	v_add_f32_e32 v143, v143, v143
	v_exp_f32_e32 v143, v143
	s_nop 0
	v_add_f32_e32 v143, 1.0, v143
	v_rcp_f32_e32 v143, v143
	s_nop 0
	v_fma_f32 v143, v143, -2.0, 1.0
	v_and_b32_e32 v123, 0xffff0000, v123
	v_fmac_f32_e32 v121, v41, v123
	v_mul_f32_e32 v123, 0x3d372713, v121
	v_mul_f32_e32 v123, v121, v123
	v_fma_f32 v123, v121, v123, v121
	v_mul_f32_e32 v123, 0x3f4c422a, v123
	v_mul_f32_e64 v144, |v123|, s76
	v_add_f32_e32 v144, v144, v144
	v_exp_f32_e32 v144, v144
	s_nop 0
	v_add_f32_e32 v144, 1.0, v144
	v_rcp_f32_e32 v144, v144
	s_nop 0
	v_fma_f32 v144, v144, -2.0, 1.0
	v_and_b32_e32 v125, 0xffff0000, v125
	v_fmac_f32_e32 v117, v29, v125
	v_mul_f32_e32 v125, 0x3d372713, v117
	v_mul_f32_e32 v125, v117, v125
	v_fma_f32 v125, v117, v125, v117
	v_mul_f32_e32 v125, 0x3f4c422a, v125
	v_mul_f32_e64 v145, |v125|, s76
	v_add_f32_e32 v145, v145, v145
	v_exp_f32_e32 v145, v145
	s_nop 0
	v_add_f32_e32 v145, 1.0, v145
	v_rcp_f32_e32 v145, v145
	s_nop 0
	v_fma_f32 v145, v145, -2.0, 1.0
	v_bfi_b32 v139, s10, v140, v139
	v_mul_f32_e32 v120, 0.5, v120
	v_add_f32_e32 v139, 1.0, v139
	v_mul_f32_e32 v139, v120, v139
	v_bfi_b32 v120, s10, v144, v123
	v_mul_f32_e32 v121, 0.5, v121
	v_add_f32_e32 v120, 1.0, v120
	v_mul_f32_e32 v123, v121, v120
	v_bfi_b32 v120, s10, v143, v141
	v_mul_f32_e32 v116, 0.5, v116
	v_add_f32_e32 v120, 1.0, v120
	v_mul_f32_e32 v140, v116, v120
	v_bfi_b32 v120, s10, v133, v132
	v_mul_f32_e32 v114, 0.5, v114
	v_add_f32_e32 v120, 1.0, v120
	v_mul_f32_e32 v116, 0.5, v124
	v_mul_f32_e32 v124, v114, v120
	v_bfi_b32 v114, s10, v138, v115
	v_mul_f32_e32 v115, 0.5, v118
	v_bfi_b32 v118, s10, v131, v129
	v_add_f32_e32 v114, 1.0, v114
	v_add_f32_e32 v118, 1.0, v118
	v_mul_f32_e32 v116, v116, v114
	v_mul_f32_e32 v114, 0.5, v122
	v_mul_f32_e32 v122, v115, v118
	v_bfi_b32 v115, s10, v137, v119
	v_add_f32_e32 v115, 1.0, v115
	v_mul_f32_e32 v119, v114, v115
	v_bfi_b32 v114, s10, v145, v125
	v_mul_f32_e32 v117, 0.5, v117
	v_lshlrev_b32_e32 v118, 4, v128
	v_add_f32_e32 v114, 1.0, v114
	v_mul_f32_e32 v117, v117, v114
	v_or_b32_e32 v114, v118, v136
	v_ashrrev_i32_e32 v115, 31, v114
	v_lshlrev_b64 v[114:115], 10, v[114:115]
	v_lshl_add_u64 v[120:121], v[134:135], 0, v[114:115]
	v_cvt_pk_bf16_f32 v114, v122, v119
	v_cvt_pk_bf16_f32 v115, v139, v123
	v_cvt_pk_bf16_f32 v116, v124, v116
	v_cvt_pk_bf16_f32 v117, v140, v117
	global_store_dwordx4 v[120:121], v[114:117], off
	s_nop 1
	v_mov_b64_e32 v[114:115], v[196:197]
	v_mov_b64_e32 v[116:117], v[198:199]
	s_waitcnt vmcnt(14)
	v_lshlrev_b32_e32 v119, 16, v114
	v_fma_f32 v110, v38, v119, v110
	v_mul_f32_e32 v119, 0x3d372713, v110
	v_mul_f32_e32 v119, v110, v119
	v_fma_f32 v119, v110, v119, v110
	v_mul_f32_e32 v119, 0x3f4c422a, v119
	v_mul_f32_e64 v120, |v119|, s76
	v_add_f32_e32 v120, v120, v120
	v_exp_f32_e32 v120, v120
	s_nop 0
	v_add_f32_e32 v120, 1.0, v120
	v_rcp_f32_e32 v120, v120
	s_nop 0
	v_fma_f32 v120, v120, -2.0, 1.0
	v_lshlrev_b32_e32 v121, 16, v116
	v_fma_f32 v106, v26, v121, v106
	v_mul_f32_e32 v121, 0x3d372713, v106
	v_mul_f32_e32 v121, v106, v121
	v_fma_f32 v121, v106, v121, v106
	v_mul_f32_e32 v121, 0x3f4c422a, v121
	v_mul_f32_e64 v122, |v121|, s76
	v_add_f32_e32 v122, v122, v122
	v_exp_f32_e32 v122, v122
	s_nop 0
	v_add_f32_e32 v122, 1.0, v122
	v_rcp_f32_e32 v122, v122
	s_nop 0
	v_fma_f32 v122, v122, -2.0, 1.0
	v_and_b32_e32 v114, 0xffff0000, v114
	v_fma_f32 v114, v39, v114, v111
	v_mul_f32_e32 v111, 0x3d372713, v114
	v_mul_f32_e32 v111, v114, v111
	v_fma_f32 v111, v114, v111, v114
	v_mul_f32_e32 v111, 0x3f4c422a, v111
	v_mul_f32_e64 v123, |v111|, s76
	v_add_f32_e32 v123, v123, v123
	v_exp_f32_e32 v123, v123
	s_nop 0
	v_add_f32_e32 v123, 1.0, v123
	v_rcp_f32_e32 v123, v123
	s_nop 0
	v_fma_f32 v123, v123, -2.0, 1.0
	v_and_b32_e32 v116, 0xffff0000, v116
	v_fma_f32 v116, v27, v116, v107
	v_mul_f32_e32 v107, 0x3d372713, v116
	v_mul_f32_e32 v107, v116, v107
	v_fma_f32 v107, v116, v107, v116
	v_mul_f32_e32 v107, 0x3f4c422a, v107
	v_mul_f32_e64 v124, |v107|, s76
	v_add_f32_e32 v124, v124, v124
	v_exp_f32_e32 v124, v124
	s_nop 0
	v_add_f32_e32 v124, 1.0, v124
	v_rcp_f32_e32 v124, v124
	s_nop 0
	v_fma_f32 v124, v124, -2.0, 1.0
	v_lshlrev_b32_e32 v125, 16, v115
	v_fma_f32 v112, v40, v125, v112
	v_mul_f32_e32 v125, 0x3d372713, v112
	v_mul_f32_e32 v125, v112, v125
	v_fma_f32 v125, v112, v125, v112
	v_mul_f32_e32 v125, 0x3f4c422a, v125
	v_mul_f32_e64 v126, |v125|, s76
	v_add_f32_e32 v126, v126, v126
	v_exp_f32_e32 v126, v126
	s_nop 0
	v_add_f32_e32 v126, 1.0, v126
	v_rcp_f32_e32 v126, v126
	s_nop 0
	v_fma_f32 v126, v126, -2.0, 1.0
	v_lshlrev_b32_e32 v127, 16, v117
	v_fma_f32 v108, v28, v127, v108
	v_mul_f32_e32 v127, 0x3d372713, v108
	v_mul_f32_e32 v127, v108, v127
	v_fma_f32 v127, v108, v127, v108
	v_mul_f32_e32 v127, 0x3f4c422a, v127
	v_mul_f32_e64 v128, |v127|, s76
	v_add_f32_e32 v128, v128, v128
	v_exp_f32_e32 v128, v128
	s_nop 0
	v_add_f32_e32 v128, 1.0, v128
	v_rcp_f32_e32 v128, v128
	s_nop 0
	v_fma_f32 v128, v128, -2.0, 1.0
	v_and_b32_e32 v115, 0xffff0000, v115
	v_fmac_f32_e32 v113, v41, v115
	v_mul_f32_e32 v115, 0x3d372713, v113
	v_mul_f32_e32 v115, v113, v115
	v_fma_f32 v115, v113, v115, v113
	v_mul_f32_e32 v115, 0x3f4c422a, v115
	v_mul_f32_e64 v129, |v115|, s76
	v_add_f32_e32 v129, v129, v129
	v_exp_f32_e32 v129, v129
	s_nop 0
	v_add_f32_e32 v129, 1.0, v129
	v_rcp_f32_e32 v129, v129
	s_nop 0
	v_fma_f32 v129, v129, -2.0, 1.0
	v_and_b32_e32 v117, 0xffff0000, v117
	v_fmac_f32_e32 v109, v29, v117
	v_mul_f32_e32 v117, 0x3d372713, v109
	v_mul_f32_e32 v117, v109, v117
	v_fma_f32 v117, v109, v117, v109
	v_mul_f32_e32 v117, 0x3f4c422a, v117
	v_mul_f32_e64 v131, |v117|, s76
	v_add_f32_e32 v131, v131, v131
	v_exp_f32_e32 v131, v131
	s_nop 0
	v_add_f32_e32 v131, 1.0, v131
	v_rcp_f32_e32 v131, v131
	s_nop 0
	v_fma_f32 v131, v131, -2.0, 1.0
	v_bfi_b32 v115, s10, v129, v115
	v_mul_f32_e32 v113, 0.5, v113
	v_add_f32_e32 v115, 1.0, v115
	v_mul_f32_e32 v113, v113, v115
	v_bfi_b32 v115, s10, v128, v127
	v_mul_f32_e32 v108, 0.5, v108
	v_add_f32_e32 v115, 1.0, v115
	v_mul_f32_e32 v115, v108, v115
	v_mul_f32_e32 v108, 0.5, v116
	v_bfi_b32 v116, s10, v122, v121
	v_mul_f32_e32 v106, 0.5, v106
	v_add_f32_e32 v116, 1.0, v116
	v_mul_f32_e32 v116, v106, v116
	v_bfi_b32 v106, s10, v124, v107
	v_mul_f32_e32 v107, 0.5, v110
	v_bfi_b32 v110, s10, v120, v119
	v_add_f32_e32 v106, 1.0, v106
	v_add_f32_e32 v110, 1.0, v110
	v_mul_f32_e32 v108, v108, v106
	v_mul_f32_e32 v106, 0.5, v114
	v_mul_f32_e32 v114, v107, v110
	v_bfi_b32 v107, s10, v123, v111
	v_add_f32_e32 v107, 1.0, v107
	v_mul_f32_e32 v119, v106, v107
	v_bfi_b32 v106, s10, v131, v117
	v_mul_f32_e32 v109, 0.5, v109
	v_add_f32_e32 v106, 1.0, v106
	v_bfi_b32 v125, s10, v126, v125
	v_mul_f32_e32 v109, v109, v106
	v_or_b32_e32 v106, v118, v130
	v_mul_f32_e32 v112, 0.5, v112
	v_add_f32_e32 v125, 1.0, v125
	v_ashrrev_i32_e32 v107, 31, v106
	v_mul_f32_e32 v112, v112, v125
	v_lshlrev_b64 v[106:107], 10, v[106:107]
	v_lshl_add_u64 v[110:111], v[134:135], 0, v[106:107]
	v_cvt_pk_bf16_f32 v107, v112, v113
	v_add_u32_e32 v112, 32, v142
	v_cvt_pk_bf16_f32 v106, v114, v119
	v_cvt_pk_bf16_f32 v108, v116, v108
	v_cvt_pk_bf16_f32 v109, v115, v109
	v_ashrrev_i32_e32 v113, 31, v112
	global_store_dwordx4 v[110:111], v[106:109], off
	s_nop 1
	v_lshlrev_b64 v[106:107], 9, v[112:113]
	v_lshl_add_u64 v[106:107], s[0:1], 0, v[106:107]
	v_lshl_add_u64 v[110:111], v[106:107], 0, v[0:1]
	s_nop 1
	v_mov_b64_e32 v[106:107], v[200:201]
	v_mov_b64_e32 v[108:109], v[202:203]
	s_waitcnt vmcnt(14)
	v_lshlrev_b32_e32 v113, 16, v106
	v_fma_f32 v102, v38, v113, v102
	v_mul_f32_e32 v113, 0x3d372713, v102
	v_mul_f32_e32 v113, v102, v113
	v_fma_f32 v113, v102, v113, v102
	v_mul_f32_e32 v113, 0x3f4c422a, v113
	v_mul_f32_e64 v114, |v113|, s76
	v_add_f32_e32 v114, v114, v114
	v_exp_f32_e32 v114, v114
	s_nop 0
	v_add_f32_e32 v114, 1.0, v114
	v_rcp_f32_e32 v114, v114
	s_nop 0
	v_fma_f32 v114, v114, -2.0, 1.0
	v_lshlrev_b32_e32 v115, 16, v108
	v_fma_f32 v98, v26, v115, v98
	v_mul_f32_e32 v115, 0x3d372713, v98
	v_mul_f32_e32 v115, v98, v115
	v_fma_f32 v115, v98, v115, v98
	v_mul_f32_e32 v115, 0x3f4c422a, v115
	v_mul_f32_e64 v116, |v115|, s76
	v_add_f32_e32 v116, v116, v116
	v_exp_f32_e32 v116, v116
	s_nop 0
	v_add_f32_e32 v116, 1.0, v116
	v_rcp_f32_e32 v116, v116
	s_nop 0
	v_fma_f32 v116, v116, -2.0, 1.0
	v_and_b32_e32 v106, 0xffff0000, v106
	v_fma_f32 v106, v39, v106, v103
	v_mul_f32_e32 v103, 0x3d372713, v106
	v_mul_f32_e32 v103, v106, v103
	v_fma_f32 v103, v106, v103, v106
	v_mul_f32_e32 v103, 0x3f4c422a, v103
	v_mul_f32_e64 v117, |v103|, s76
	v_add_f32_e32 v117, v117, v117
	v_exp_f32_e32 v117, v117
	s_nop 0
	v_add_f32_e32 v117, 1.0, v117
	v_rcp_f32_e32 v117, v117
	s_nop 0
	v_fma_f32 v117, v117, -2.0, 1.0
	v_and_b32_e32 v108, 0xffff0000, v108
	v_fma_f32 v108, v27, v108, v99
	v_mul_f32_e32 v99, 0x3d372713, v108
	v_mul_f32_e32 v99, v108, v99
	v_fma_f32 v99, v108, v99, v108
	v_mul_f32_e32 v99, 0x3f4c422a, v99
	v_mul_f32_e64 v118, |v99|, s76
	v_add_f32_e32 v118, v118, v118
	v_exp_f32_e32 v118, v118
	s_nop 0
	v_add_f32_e32 v118, 1.0, v118
	v_rcp_f32_e32 v118, v118
	s_nop 0
	v_fma_f32 v118, v118, -2.0, 1.0
	v_lshlrev_b32_e32 v119, 16, v107
	v_fma_f32 v104, v40, v119, v104
	v_mul_f32_e32 v119, 0x3d372713, v104
	v_mul_f32_e32 v119, v104, v119
	v_fma_f32 v119, v104, v119, v104
	v_mul_f32_e32 v119, 0x3f4c422a, v119
	v_mul_f32_e64 v120, |v119|, s76
	v_add_f32_e32 v120, v120, v120
	v_exp_f32_e32 v120, v120
	s_nop 0
	v_add_f32_e32 v120, 1.0, v120
	v_rcp_f32_e32 v120, v120
	s_nop 0
	v_fma_f32 v120, v120, -2.0, 1.0
	v_lshlrev_b32_e32 v121, 16, v109
	v_fma_f32 v100, v28, v121, v100
	v_mul_f32_e32 v121, 0x3d372713, v100
	v_mul_f32_e32 v121, v100, v121
	v_fma_f32 v121, v100, v121, v100
	v_mul_f32_e32 v121, 0x3f4c422a, v121
	v_mul_f32_e64 v122, |v121|, s76
	v_add_f32_e32 v122, v122, v122
	v_exp_f32_e32 v122, v122
	s_nop 0
	v_add_f32_e32 v122, 1.0, v122
	v_rcp_f32_e32 v122, v122
	s_nop 0
	v_fma_f32 v122, v122, -2.0, 1.0
	v_and_b32_e32 v107, 0xffff0000, v107
	v_fmac_f32_e32 v105, v41, v107
	v_mul_f32_e32 v107, 0x3d372713, v105
	v_mul_f32_e32 v107, v105, v107
	v_fma_f32 v107, v105, v107, v105
	v_mul_f32_e32 v107, 0x3f4c422a, v107
	v_mul_f32_e64 v123, |v107|, s76
	v_add_f32_e32 v123, v123, v123
	v_exp_f32_e32 v123, v123
	s_nop 0
	v_add_f32_e32 v123, 1.0, v123
	v_rcp_f32_e32 v123, v123
	s_nop 0
	v_fma_f32 v123, v123, -2.0, 1.0
	v_and_b32_e32 v109, 0xffff0000, v109
	v_fmac_f32_e32 v101, v29, v109
	v_mul_f32_e32 v109, 0x3d372713, v101
	v_mul_f32_e32 v109, v101, v109
	v_fma_f32 v109, v101, v109, v101
	v_mul_f32_e32 v109, 0x3f4c422a, v109
	v_mul_f32_e64 v124, |v109|, s76
	v_add_f32_e32 v124, v124, v124
	v_exp_f32_e32 v124, v124
	s_nop 0
	v_add_f32_e32 v124, 1.0, v124
	v_rcp_f32_e32 v124, v124
	s_nop 0
	v_fma_f32 v124, v124, -2.0, 1.0
	v_bfi_b32 v119, s10, v120, v119
	v_mul_f32_e32 v104, 0.5, v104
	v_add_f32_e32 v119, 1.0, v119
	v_mul_f32_e32 v119, v104, v119
	v_bfi_b32 v104, s10, v123, v107
	v_mul_f32_e32 v105, 0.5, v105
	v_add_f32_e32 v104, 1.0, v104
	v_mul_f32_e32 v107, v105, v104
	v_bfi_b32 v104, s10, v122, v121
	v_mul_f32_e32 v100, 0.5, v100
	v_add_f32_e32 v104, 1.0, v104
	v_mul_f32_e32 v120, v100, v104
	v_bfi_b32 v104, s10, v116, v115
	v_mul_f32_e32 v98, 0.5, v98
	v_add_f32_e32 v104, 1.0, v104
	v_mul_f32_e32 v100, 0.5, v108
	v_mul_f32_e32 v108, v98, v104
	v_bfi_b32 v98, s10, v118, v99
	v_mul_f32_e32 v99, 0.5, v102
	v_bfi_b32 v102, s10, v114, v113
	v_add_f32_e32 v98, 1.0, v98
	v_add_f32_e32 v102, 1.0, v102
	v_mul_f32_e32 v100, v100, v98
	v_mul_f32_e32 v98, 0.5, v106
	v_mul_f32_e32 v106, v99, v102
	v_bfi_b32 v99, s10, v117, v103
	v_add_f32_e32 v99, 1.0, v99
	v_mul_f32_e32 v103, v98, v99
	v_bfi_b32 v98, s10, v124, v109
	v_mul_f32_e32 v101, 0.5, v101
	v_lshlrev_b32_e32 v102, 4, v112
	v_add_f32_e32 v98, 1.0, v98
	v_mul_f32_e32 v101, v101, v98
	v_or_b32_e32 v98, v102, v136
	v_ashrrev_i32_e32 v99, 31, v98
	v_lshlrev_b64 v[98:99], 10, v[98:99]
	v_lshl_add_u64 v[104:105], v[134:135], 0, v[98:99]
	v_cvt_pk_bf16_f32 v98, v106, v103
	v_cvt_pk_bf16_f32 v99, v119, v107
	v_cvt_pk_bf16_f32 v100, v108, v100
	v_cvt_pk_bf16_f32 v101, v120, v101
	global_store_dwordx4 v[104:105], v[98:101], off
	s_nop 1
	v_mov_b64_e32 v[98:99], v[204:205]
	v_mov_b64_e32 v[100:101], v[206:207]
	s_waitcnt vmcnt(14)
	v_lshlrev_b32_e32 v103, 16, v98
	v_fma_f32 v94, v38, v103, v94
	v_mul_f32_e32 v103, 0x3d372713, v94
	v_mul_f32_e32 v103, v94, v103
	v_fma_f32 v103, v94, v103, v94
	v_mul_f32_e32 v103, 0x3f4c422a, v103
	v_mul_f32_e64 v104, |v103|, s76
	v_add_f32_e32 v104, v104, v104
	v_exp_f32_e32 v104, v104
	s_nop 0
	v_add_f32_e32 v104, 1.0, v104
	v_rcp_f32_e32 v104, v104
	s_nop 0
	v_fma_f32 v104, v104, -2.0, 1.0
	v_lshlrev_b32_e32 v105, 16, v100
	v_fma_f32 v90, v26, v105, v90
	v_mul_f32_e32 v105, 0x3d372713, v90
	v_mul_f32_e32 v105, v90, v105
	v_fma_f32 v105, v90, v105, v90
	v_mul_f32_e32 v105, 0x3f4c422a, v105
	v_mul_f32_e64 v106, |v105|, s76
	v_add_f32_e32 v106, v106, v106
	v_exp_f32_e32 v106, v106
	s_nop 0
	v_add_f32_e32 v106, 1.0, v106
	v_rcp_f32_e32 v106, v106
	s_nop 0
	v_fma_f32 v106, v106, -2.0, 1.0
	v_and_b32_e32 v98, 0xffff0000, v98
	v_fma_f32 v98, v39, v98, v95
	v_mul_f32_e32 v95, 0x3d372713, v98
	v_mul_f32_e32 v95, v98, v95
	v_fma_f32 v95, v98, v95, v98
	v_mul_f32_e32 v95, 0x3f4c422a, v95
	v_mul_f32_e64 v107, |v95|, s76
	v_add_f32_e32 v107, v107, v107
	v_exp_f32_e32 v107, v107
	s_nop 0
	v_add_f32_e32 v107, 1.0, v107
	v_rcp_f32_e32 v107, v107
	s_nop 0
	v_fma_f32 v107, v107, -2.0, 1.0
	v_and_b32_e32 v100, 0xffff0000, v100
	v_fma_f32 v100, v27, v100, v91
	v_mul_f32_e32 v91, 0x3d372713, v100
	v_mul_f32_e32 v91, v100, v91
	v_fma_f32 v91, v100, v91, v100
	v_mul_f32_e32 v91, 0x3f4c422a, v91
	v_mul_f32_e64 v108, |v91|, s76
	v_add_f32_e32 v108, v108, v108
	v_exp_f32_e32 v108, v108
	s_nop 0
	v_add_f32_e32 v108, 1.0, v108
	v_rcp_f32_e32 v108, v108
	s_nop 0
	v_fma_f32 v108, v108, -2.0, 1.0
	v_lshlrev_b32_e32 v109, 16, v99
	v_fma_f32 v96, v40, v109, v96
	v_mul_f32_e32 v109, 0x3d372713, v96
	v_mul_f32_e32 v109, v96, v109
	v_fma_f32 v109, v96, v109, v96
	v_mul_f32_e32 v109, 0x3f4c422a, v109
	v_mul_f32_e64 v110, |v109|, s76
	v_add_f32_e32 v110, v110, v110
	v_exp_f32_e32 v110, v110
	s_nop 0
	v_add_f32_e32 v110, 1.0, v110
	v_rcp_f32_e32 v110, v110
	s_nop 0
	v_fma_f32 v110, v110, -2.0, 1.0
	v_lshlrev_b32_e32 v111, 16, v101
	v_fma_f32 v92, v28, v111, v92
	v_mul_f32_e32 v111, 0x3d372713, v92
	v_mul_f32_e32 v111, v92, v111
	v_fma_f32 v111, v92, v111, v92
	v_mul_f32_e32 v111, 0x3f4c422a, v111
	v_mul_f32_e64 v112, |v111|, s76
	v_add_f32_e32 v112, v112, v112
	v_exp_f32_e32 v112, v112
	s_nop 0
	v_add_f32_e32 v112, 1.0, v112
	v_rcp_f32_e32 v112, v112
	s_nop 0
	v_fma_f32 v112, v112, -2.0, 1.0
	v_and_b32_e32 v99, 0xffff0000, v99
	v_fmac_f32_e32 v97, v41, v99
	v_mul_f32_e32 v99, 0x3d372713, v97
	v_mul_f32_e32 v99, v97, v99
	v_fma_f32 v99, v97, v99, v97
	v_mul_f32_e32 v99, 0x3f4c422a, v99
	v_mul_f32_e64 v113, |v99|, s76
	v_add_f32_e32 v113, v113, v113
	v_exp_f32_e32 v113, v113
	s_nop 0
	v_add_f32_e32 v113, 1.0, v113
	v_rcp_f32_e32 v113, v113
	s_nop 0
	v_fma_f32 v113, v113, -2.0, 1.0
	v_and_b32_e32 v101, 0xffff0000, v101
	v_fmac_f32_e32 v93, v29, v101
	v_mul_f32_e32 v101, 0x3d372713, v93
	v_mul_f32_e32 v101, v93, v101
	v_fma_f32 v101, v93, v101, v93
	v_mul_f32_e32 v101, 0x3f4c422a, v101
	v_mul_f32_e64 v114, |v101|, s76
	v_add_f32_e32 v114, v114, v114
	v_exp_f32_e32 v114, v114
	s_nop 0
	v_add_f32_e32 v114, 1.0, v114
	v_rcp_f32_e32 v114, v114
	s_nop 0
	v_fma_f32 v114, v114, -2.0, 1.0
	v_bfi_b32 v99, s10, v113, v99
	v_mul_f32_e32 v97, 0.5, v97
	v_add_f32_e32 v99, 1.0, v99
	v_mul_f32_e32 v97, v97, v99
	v_bfi_b32 v99, s10, v112, v111
	v_mul_f32_e32 v92, 0.5, v92
	v_add_f32_e32 v99, 1.0, v99
	v_mul_f32_e32 v99, v92, v99
	v_mul_f32_e32 v92, 0.5, v100
	v_bfi_b32 v100, s10, v106, v105
	v_mul_f32_e32 v90, 0.5, v90
	v_add_f32_e32 v100, 1.0, v100
	v_mul_f32_e32 v100, v90, v100
	v_bfi_b32 v90, s10, v108, v91
	v_mul_f32_e32 v91, 0.5, v94
	v_bfi_b32 v94, s10, v104, v103
	v_add_f32_e32 v90, 1.0, v90
	v_add_f32_e32 v94, 1.0, v94
	v_mul_f32_e32 v92, v92, v90
	v_mul_f32_e32 v90, 0.5, v98
	v_mul_f32_e32 v98, v91, v94
	v_bfi_b32 v91, s10, v107, v95
	v_add_f32_e32 v91, 1.0, v91
	v_mul_f32_e32 v103, v90, v91
	v_bfi_b32 v90, s10, v114, v101
	v_mul_f32_e32 v93, 0.5, v93
	v_add_f32_e32 v90, 1.0, v90
	v_bfi_b32 v109, s10, v110, v109
	v_mul_f32_e32 v93, v93, v90
	v_or_b32_e32 v90, v102, v130
	v_mul_f32_e32 v96, 0.5, v96
	v_add_f32_e32 v109, 1.0, v109
	v_ashrrev_i32_e32 v91, 31, v90
	v_mul_f32_e32 v96, v96, v109
	v_lshlrev_b64 v[90:91], 10, v[90:91]
	v_lshl_add_u64 v[94:95], v[134:135], 0, v[90:91]
	v_cvt_pk_bf16_f32 v91, v96, v97
	v_add_u32_e32 v96, 48, v142
	v_cvt_pk_bf16_f32 v90, v98, v103
	v_cvt_pk_bf16_f32 v92, v100, v92
	v_cvt_pk_bf16_f32 v93, v99, v93
	v_ashrrev_i32_e32 v97, 31, v96
	global_store_dwordx4 v[94:95], v[90:93], off
	s_nop 1
	v_lshlrev_b64 v[90:91], 9, v[96:97]
	v_lshl_add_u64 v[90:91], s[0:1], 0, v[90:91]
	v_lshl_add_u64 v[94:95], v[90:91], 0, v[0:1]
	s_nop 1
	v_mov_b64_e32 v[90:91], v[208:209]
	v_mov_b64_e32 v[92:93], v[210:211]
	s_waitcnt vmcnt(14)
	v_lshlrev_b32_e32 v97, 16, v90
	v_fma_f32 v86, v38, v97, v86
	v_mul_f32_e32 v97, 0x3d372713, v86
	v_mul_f32_e32 v97, v86, v97
	v_fma_f32 v97, v86, v97, v86
	v_mul_f32_e32 v97, 0x3f4c422a, v97
	v_mul_f32_e64 v98, |v97|, s76
	v_add_f32_e32 v98, v98, v98
	v_exp_f32_e32 v98, v98
	s_nop 0
	v_add_f32_e32 v98, 1.0, v98
	v_rcp_f32_e32 v98, v98
	s_nop 0
	v_fma_f32 v98, v98, -2.0, 1.0
	v_lshlrev_b32_e32 v99, 16, v92
	v_fma_f32 v82, v26, v99, v82
	v_mul_f32_e32 v99, 0x3d372713, v82
	v_mul_f32_e32 v99, v82, v99
	v_fma_f32 v99, v82, v99, v82
	v_mul_f32_e32 v99, 0x3f4c422a, v99
	v_mul_f32_e64 v100, |v99|, s76
	v_add_f32_e32 v100, v100, v100
	v_exp_f32_e32 v100, v100
	s_nop 0
	v_add_f32_e32 v100, 1.0, v100
	v_rcp_f32_e32 v100, v100
	s_nop 0
	v_fma_f32 v100, v100, -2.0, 1.0
	v_and_b32_e32 v90, 0xffff0000, v90
	v_fma_f32 v90, v39, v90, v87
	v_mul_f32_e32 v87, 0x3d372713, v90
	v_mul_f32_e32 v87, v90, v87
	v_fma_f32 v87, v90, v87, v90
	v_mul_f32_e32 v87, 0x3f4c422a, v87
	v_mul_f32_e64 v101, |v87|, s76
	v_add_f32_e32 v101, v101, v101
	v_exp_f32_e32 v101, v101
	s_nop 0
	v_add_f32_e32 v101, 1.0, v101
	v_rcp_f32_e32 v101, v101
	s_nop 0
	v_fma_f32 v101, v101, -2.0, 1.0
	v_and_b32_e32 v92, 0xffff0000, v92
	v_fma_f32 v92, v27, v92, v83
	v_mul_f32_e32 v83, 0x3d372713, v92
	v_mul_f32_e32 v83, v92, v83
	v_fma_f32 v83, v92, v83, v92
	v_mul_f32_e32 v83, 0x3f4c422a, v83
	v_mul_f32_e64 v102, |v83|, s76
	v_add_f32_e32 v102, v102, v102
	v_exp_f32_e32 v102, v102
	s_nop 0
	v_add_f32_e32 v102, 1.0, v102
	v_rcp_f32_e32 v102, v102
	s_nop 0
	v_fma_f32 v102, v102, -2.0, 1.0
	v_lshlrev_b32_e32 v103, 16, v91
	v_fma_f32 v88, v40, v103, v88
	v_mul_f32_e32 v103, 0x3d372713, v88
	v_mul_f32_e32 v103, v88, v103
	v_fma_f32 v103, v88, v103, v88
	v_mul_f32_e32 v103, 0x3f4c422a, v103
	v_mul_f32_e64 v104, |v103|, s76
	v_add_f32_e32 v104, v104, v104
	v_exp_f32_e32 v104, v104
	s_nop 0
	v_add_f32_e32 v104, 1.0, v104
	v_rcp_f32_e32 v104, v104
	s_nop 0
	v_fma_f32 v104, v104, -2.0, 1.0
	v_lshlrev_b32_e32 v105, 16, v93
	v_fma_f32 v84, v28, v105, v84
	v_mul_f32_e32 v105, 0x3d372713, v84
	v_mul_f32_e32 v105, v84, v105
	v_fma_f32 v105, v84, v105, v84
	v_mul_f32_e32 v105, 0x3f4c422a, v105
	v_mul_f32_e64 v106, |v105|, s76
	v_add_f32_e32 v106, v106, v106
	v_exp_f32_e32 v106, v106
	s_nop 0
	v_add_f32_e32 v106, 1.0, v106
	v_rcp_f32_e32 v106, v106
	s_nop 0
	v_fma_f32 v106, v106, -2.0, 1.0
	v_and_b32_e32 v91, 0xffff0000, v91
	v_fmac_f32_e32 v89, v41, v91
	v_mul_f32_e32 v91, 0x3d372713, v89
	v_mul_f32_e32 v91, v89, v91
	v_fma_f32 v91, v89, v91, v89
	v_mul_f32_e32 v91, 0x3f4c422a, v91
	v_mul_f32_e64 v107, |v91|, s76
	v_add_f32_e32 v107, v107, v107
	v_exp_f32_e32 v107, v107
	s_nop 0
	v_add_f32_e32 v107, 1.0, v107
	v_rcp_f32_e32 v107, v107
	s_nop 0
	v_fma_f32 v107, v107, -2.0, 1.0
	v_and_b32_e32 v93, 0xffff0000, v93
	v_fmac_f32_e32 v85, v29, v93
	v_mul_f32_e32 v93, 0x3d372713, v85
	v_mul_f32_e32 v93, v85, v93
	v_fma_f32 v93, v85, v93, v85
	v_mul_f32_e32 v93, 0x3f4c422a, v93
	v_mul_f32_e64 v108, |v93|, s76
	v_add_f32_e32 v108, v108, v108
	v_exp_f32_e32 v108, v108
	s_nop 0
	v_add_f32_e32 v108, 1.0, v108
	v_rcp_f32_e32 v108, v108
	s_nop 0
	v_fma_f32 v108, v108, -2.0, 1.0
	v_bfi_b32 v103, s10, v104, v103
	v_mul_f32_e32 v88, 0.5, v88
	v_add_f32_e32 v103, 1.0, v103
	v_mul_f32_e32 v103, v88, v103
	v_bfi_b32 v88, s10, v107, v91
	v_mul_f32_e32 v89, 0.5, v89
	v_add_f32_e32 v88, 1.0, v88
	v_mul_f32_e32 v91, v89, v88
	v_bfi_b32 v88, s10, v106, v105
	v_mul_f32_e32 v84, 0.5, v84
	v_add_f32_e32 v88, 1.0, v88
	v_mul_f32_e32 v104, v84, v88
	v_bfi_b32 v88, s10, v100, v99
	v_mul_f32_e32 v82, 0.5, v82
	v_add_f32_e32 v88, 1.0, v88
	v_mul_f32_e32 v84, 0.5, v92
	v_mul_f32_e32 v92, v82, v88
	v_bfi_b32 v82, s10, v102, v83
	v_mul_f32_e32 v83, 0.5, v86
	v_bfi_b32 v86, s10, v98, v97
	v_add_f32_e32 v82, 1.0, v82
	v_add_f32_e32 v86, 1.0, v86
	v_mul_f32_e32 v84, v84, v82
	v_mul_f32_e32 v82, 0.5, v90
	v_mul_f32_e32 v90, v83, v86
	v_bfi_b32 v83, s10, v101, v87
	v_add_f32_e32 v83, 1.0, v83
	v_mul_f32_e32 v87, v82, v83
	v_bfi_b32 v82, s10, v108, v93
	v_mul_f32_e32 v85, 0.5, v85
	v_lshlrev_b32_e32 v86, 4, v96
	v_add_f32_e32 v82, 1.0, v82
	v_mul_f32_e32 v85, v85, v82
	v_or_b32_e32 v82, v86, v136
	v_ashrrev_i32_e32 v83, 31, v82
	v_lshlrev_b64 v[82:83], 10, v[82:83]
	v_lshl_add_u64 v[88:89], v[134:135], 0, v[82:83]
	v_cvt_pk_bf16_f32 v82, v90, v87
	v_cvt_pk_bf16_f32 v83, v103, v91
	v_cvt_pk_bf16_f32 v84, v92, v84
	v_cvt_pk_bf16_f32 v85, v104, v85
	global_store_dwordx4 v[88:89], v[82:85], off
	s_nop 1
	v_mov_b64_e32 v[82:83], v[212:213]
	v_mov_b64_e32 v[84:85], v[214:215]
	s_waitcnt vmcnt(14)
	v_lshlrev_b32_e32 v87, 16, v82
	v_fma_f32 v78, v38, v87, v78
	v_mul_f32_e32 v87, 0x3d372713, v78
	v_mul_f32_e32 v87, v78, v87
	v_fma_f32 v87, v78, v87, v78
	v_mul_f32_e32 v87, 0x3f4c422a, v87
	v_mul_f32_e64 v88, |v87|, s76
	v_add_f32_e32 v88, v88, v88
	v_exp_f32_e32 v88, v88
	s_nop 0
	v_add_f32_e32 v88, 1.0, v88
	v_rcp_f32_e32 v88, v88
	s_nop 0
	v_fma_f32 v88, v88, -2.0, 1.0
	v_lshlrev_b32_e32 v89, 16, v84
	v_fma_f32 v74, v26, v89, v74
	v_mul_f32_e32 v89, 0x3d372713, v74
	v_mul_f32_e32 v89, v74, v89
	v_fma_f32 v89, v74, v89, v74
	v_mul_f32_e32 v89, 0x3f4c422a, v89
	v_mul_f32_e64 v90, |v89|, s76
	v_add_f32_e32 v90, v90, v90
	v_exp_f32_e32 v90, v90
	s_nop 0
	v_add_f32_e32 v90, 1.0, v90
	v_rcp_f32_e32 v90, v90
	s_nop 0
	v_fma_f32 v90, v90, -2.0, 1.0
	v_and_b32_e32 v82, 0xffff0000, v82
	v_fma_f32 v82, v39, v82, v79
	v_mul_f32_e32 v79, 0x3d372713, v82
	v_mul_f32_e32 v79, v82, v79
	v_fma_f32 v79, v82, v79, v82
	v_mul_f32_e32 v79, 0x3f4c422a, v79
	v_mul_f32_e64 v91, |v79|, s76
	v_add_f32_e32 v91, v91, v91
	v_exp_f32_e32 v91, v91
	s_nop 0
	v_add_f32_e32 v91, 1.0, v91
	v_rcp_f32_e32 v91, v91
	s_nop 0
	v_fma_f32 v91, v91, -2.0, 1.0
	v_and_b32_e32 v84, 0xffff0000, v84
	v_fma_f32 v84, v27, v84, v75
	v_mul_f32_e32 v75, 0x3d372713, v84
	v_mul_f32_e32 v75, v84, v75
	v_fma_f32 v75, v84, v75, v84
	v_mul_f32_e32 v75, 0x3f4c422a, v75
	v_mul_f32_e64 v92, |v75|, s76
	v_add_f32_e32 v92, v92, v92
	v_exp_f32_e32 v92, v92
	s_nop 0
	v_add_f32_e32 v92, 1.0, v92
	v_rcp_f32_e32 v92, v92
	s_nop 0
	v_fma_f32 v92, v92, -2.0, 1.0
	v_lshlrev_b32_e32 v93, 16, v83
	v_fma_f32 v80, v40, v93, v80
	v_mul_f32_e32 v93, 0x3d372713, v80
	v_mul_f32_e32 v93, v80, v93
	v_fma_f32 v93, v80, v93, v80
	v_mul_f32_e32 v93, 0x3f4c422a, v93
	v_mul_f32_e64 v94, |v93|, s76
	v_add_f32_e32 v94, v94, v94
	v_exp_f32_e32 v94, v94
	s_nop 0
	v_add_f32_e32 v94, 1.0, v94
	v_rcp_f32_e32 v94, v94
	s_nop 0
	v_fma_f32 v94, v94, -2.0, 1.0
	v_lshlrev_b32_e32 v95, 16, v85
	v_fma_f32 v76, v28, v95, v76
	v_mul_f32_e32 v95, 0x3d372713, v76
	v_mul_f32_e32 v95, v76, v95
	v_fma_f32 v95, v76, v95, v76
	v_mul_f32_e32 v95, 0x3f4c422a, v95
	v_mul_f32_e64 v96, |v95|, s76
	v_add_f32_e32 v96, v96, v96
	v_exp_f32_e32 v96, v96
	s_nop 0
	v_add_f32_e32 v96, 1.0, v96
	v_rcp_f32_e32 v96, v96
	s_nop 0
	v_fma_f32 v96, v96, -2.0, 1.0
	v_and_b32_e32 v83, 0xffff0000, v83
	v_fmac_f32_e32 v81, v41, v83
	v_mul_f32_e32 v83, 0x3d372713, v81
	v_mul_f32_e32 v83, v81, v83
	v_fma_f32 v83, v81, v83, v81
	v_mul_f32_e32 v83, 0x3f4c422a, v83
	v_mul_f32_e64 v97, |v83|, s76
	v_add_f32_e32 v97, v97, v97
	v_exp_f32_e32 v97, v97
	s_nop 0
	v_add_f32_e32 v97, 1.0, v97
	v_rcp_f32_e32 v97, v97
	s_nop 0
	v_fma_f32 v97, v97, -2.0, 1.0
	v_and_b32_e32 v85, 0xffff0000, v85
	v_fmac_f32_e32 v77, v29, v85
	v_mul_f32_e32 v85, 0x3d372713, v77
	v_mul_f32_e32 v85, v77, v85
	v_fma_f32 v85, v77, v85, v77
	v_mul_f32_e32 v85, 0x3f4c422a, v85
	v_mul_f32_e64 v98, |v85|, s76
	v_add_f32_e32 v98, v98, v98
	v_exp_f32_e32 v98, v98
	s_nop 0
	v_add_f32_e32 v98, 1.0, v98
	v_rcp_f32_e32 v98, v98
	s_nop 0
	v_fma_f32 v98, v98, -2.0, 1.0
	v_bfi_b32 v83, s10, v97, v83
	v_mul_f32_e32 v81, 0.5, v81
	v_add_f32_e32 v83, 1.0, v83
	v_mul_f32_e32 v81, v81, v83
	v_bfi_b32 v83, s10, v96, v95
	v_mul_f32_e32 v76, 0.5, v76
	v_add_f32_e32 v83, 1.0, v83
	v_mul_f32_e32 v83, v76, v83
	v_mul_f32_e32 v76, 0.5, v84
	v_bfi_b32 v84, s10, v90, v89
	v_mul_f32_e32 v74, 0.5, v74
	v_add_f32_e32 v84, 1.0, v84
	v_mul_f32_e32 v84, v74, v84
	v_bfi_b32 v74, s10, v92, v75
	v_mul_f32_e32 v75, 0.5, v78
	v_bfi_b32 v78, s10, v88, v87
	v_add_f32_e32 v74, 1.0, v74
	v_add_f32_e32 v78, 1.0, v78
	v_mul_f32_e32 v76, v76, v74
	v_mul_f32_e32 v74, 0.5, v82
	v_mul_f32_e32 v82, v75, v78
	v_bfi_b32 v75, s10, v91, v79
	v_add_f32_e32 v75, 1.0, v75
	v_mul_f32_e32 v87, v74, v75
	v_bfi_b32 v74, s10, v98, v85
	v_mul_f32_e32 v77, 0.5, v77
	v_add_f32_e32 v74, 1.0, v74
	v_bfi_b32 v93, s10, v94, v93
	v_mul_f32_e32 v77, v77, v74
	v_or_b32_e32 v74, v86, v130
	v_mul_f32_e32 v80, 0.5, v80
	v_add_f32_e32 v93, 1.0, v93
	v_ashrrev_i32_e32 v75, 31, v74
	v_mul_f32_e32 v80, v80, v93
	v_lshlrev_b64 v[74:75], 10, v[74:75]
	v_lshl_add_u64 v[78:79], v[134:135], 0, v[74:75]
	v_cvt_pk_bf16_f32 v75, v80, v81
	v_add_u32_e32 v80, 0x80, v142
	v_cvt_pk_bf16_f32 v74, v82, v87
	v_cvt_pk_bf16_f32 v76, v84, v76
	v_cvt_pk_bf16_f32 v77, v83, v77
	v_ashrrev_i32_e32 v81, 31, v80
	global_store_dwordx4 v[78:79], v[74:77], off
	s_nop 1
	v_lshlrev_b64 v[74:75], 9, v[80:81]
	v_lshl_add_u64 v[74:75], s[0:1], 0, v[74:75]
	v_lshl_add_u64 v[78:79], v[74:75], 0, v[0:1]
	s_nop 1
	v_mov_b64_e32 v[74:75], v[216:217]
	v_mov_b64_e32 v[76:77], v[218:219]
	s_waitcnt vmcnt(14)
	v_lshlrev_b32_e32 v81, 16, v74
	v_fma_f32 v70, v38, v81, v70
	v_mul_f32_e32 v81, 0x3d372713, v70
	v_mul_f32_e32 v81, v70, v81
	v_fma_f32 v81, v70, v81, v70
	v_mul_f32_e32 v81, 0x3f4c422a, v81
	v_mul_f32_e64 v82, |v81|, s76
	v_add_f32_e32 v82, v82, v82
	v_exp_f32_e32 v82, v82
	s_nop 0
	v_add_f32_e32 v82, 1.0, v82
	v_rcp_f32_e32 v82, v82
	s_nop 0
	v_fma_f32 v82, v82, -2.0, 1.0
	v_lshlrev_b32_e32 v83, 16, v76
	v_fma_f32 v66, v26, v83, v66
	v_mul_f32_e32 v83, 0x3d372713, v66
	v_mul_f32_e32 v83, v66, v83
	v_fma_f32 v83, v66, v83, v66
	v_mul_f32_e32 v83, 0x3f4c422a, v83
	v_mul_f32_e64 v84, |v83|, s76
	v_add_f32_e32 v84, v84, v84
	v_exp_f32_e32 v84, v84
	s_nop 0
	v_add_f32_e32 v84, 1.0, v84
	v_rcp_f32_e32 v84, v84
	s_nop 0
	v_fma_f32 v84, v84, -2.0, 1.0
	v_and_b32_e32 v74, 0xffff0000, v74
	v_fma_f32 v74, v39, v74, v71
	v_mul_f32_e32 v71, 0x3d372713, v74
	v_mul_f32_e32 v71, v74, v71
	v_fma_f32 v71, v74, v71, v74
	v_mul_f32_e32 v71, 0x3f4c422a, v71
	v_mul_f32_e64 v85, |v71|, s76
	v_add_f32_e32 v85, v85, v85
	v_exp_f32_e32 v85, v85
	s_nop 0
	v_add_f32_e32 v85, 1.0, v85
	v_rcp_f32_e32 v85, v85
	s_nop 0
	v_fma_f32 v85, v85, -2.0, 1.0
	v_and_b32_e32 v76, 0xffff0000, v76
	v_fma_f32 v76, v27, v76, v67
	v_mul_f32_e32 v67, 0x3d372713, v76
	v_mul_f32_e32 v67, v76, v67
	v_fma_f32 v67, v76, v67, v76
	v_mul_f32_e32 v67, 0x3f4c422a, v67
	v_mul_f32_e64 v86, |v67|, s76
	v_add_f32_e32 v86, v86, v86
	v_exp_f32_e32 v86, v86
	s_nop 0
	v_add_f32_e32 v86, 1.0, v86
	v_rcp_f32_e32 v86, v86
	s_nop 0
	v_fma_f32 v86, v86, -2.0, 1.0
	v_lshlrev_b32_e32 v87, 16, v75
	v_fma_f32 v72, v40, v87, v72
	v_mul_f32_e32 v87, 0x3d372713, v72
	v_mul_f32_e32 v87, v72, v87
	v_fma_f32 v87, v72, v87, v72
	v_mul_f32_e32 v87, 0x3f4c422a, v87
	v_mul_f32_e64 v88, |v87|, s76
	v_add_f32_e32 v88, v88, v88
	v_exp_f32_e32 v88, v88
	s_nop 0
	v_add_f32_e32 v88, 1.0, v88
	v_rcp_f32_e32 v88, v88
	s_nop 0
	v_fma_f32 v88, v88, -2.0, 1.0
	v_lshlrev_b32_e32 v89, 16, v77
	v_fma_f32 v68, v28, v89, v68
	v_mul_f32_e32 v89, 0x3d372713, v68
	v_mul_f32_e32 v89, v68, v89
	v_fma_f32 v89, v68, v89, v68
	v_mul_f32_e32 v89, 0x3f4c422a, v89
	v_mul_f32_e64 v90, |v89|, s76
	v_add_f32_e32 v90, v90, v90
	v_exp_f32_e32 v90, v90
	s_nop 0
	v_add_f32_e32 v90, 1.0, v90
	v_rcp_f32_e32 v90, v90
	s_nop 0
	v_fma_f32 v90, v90, -2.0, 1.0
	v_and_b32_e32 v75, 0xffff0000, v75
	v_fmac_f32_e32 v73, v41, v75
	v_mul_f32_e32 v75, 0x3d372713, v73
	v_mul_f32_e32 v75, v73, v75
	v_fma_f32 v75, v73, v75, v73
	v_mul_f32_e32 v75, 0x3f4c422a, v75
	v_mul_f32_e64 v91, |v75|, s76
	v_add_f32_e32 v91, v91, v91
	v_exp_f32_e32 v91, v91
	s_nop 0
	v_add_f32_e32 v91, 1.0, v91
	v_rcp_f32_e32 v91, v91
	s_nop 0
	v_fma_f32 v91, v91, -2.0, 1.0
	v_and_b32_e32 v77, 0xffff0000, v77
	v_fmac_f32_e32 v69, v29, v77
	v_mul_f32_e32 v77, 0x3d372713, v69
	v_mul_f32_e32 v77, v69, v77
	v_fma_f32 v77, v69, v77, v69
	v_mul_f32_e32 v77, 0x3f4c422a, v77
	v_mul_f32_e64 v92, |v77|, s76
	v_add_f32_e32 v92, v92, v92
	v_exp_f32_e32 v92, v92
	s_nop 0
	v_add_f32_e32 v92, 1.0, v92
	v_rcp_f32_e32 v92, v92
	s_nop 0
	v_fma_f32 v92, v92, -2.0, 1.0
	v_bfi_b32 v87, s10, v88, v87
	v_mul_f32_e32 v72, 0.5, v72
	v_add_f32_e32 v87, 1.0, v87
	v_mul_f32_e32 v87, v72, v87
	v_bfi_b32 v72, s10, v91, v75
	v_mul_f32_e32 v73, 0.5, v73
	v_add_f32_e32 v72, 1.0, v72
	v_mul_f32_e32 v75, v73, v72
	v_bfi_b32 v72, s10, v90, v89
	v_mul_f32_e32 v68, 0.5, v68
	v_add_f32_e32 v72, 1.0, v72
	v_mul_f32_e32 v88, v68, v72
	v_bfi_b32 v72, s10, v84, v83
	v_mul_f32_e32 v66, 0.5, v66
	v_add_f32_e32 v72, 1.0, v72
	v_mul_f32_e32 v68, 0.5, v76
	v_mul_f32_e32 v76, v66, v72
	v_bfi_b32 v66, s10, v86, v67
	v_mul_f32_e32 v67, 0.5, v70
	v_bfi_b32 v70, s10, v82, v81
	v_add_f32_e32 v66, 1.0, v66
	v_add_f32_e32 v70, 1.0, v70
	v_mul_f32_e32 v68, v68, v66
	v_mul_f32_e32 v66, 0.5, v74
	v_mul_f32_e32 v74, v67, v70
	v_bfi_b32 v67, s10, v85, v71
	v_add_f32_e32 v67, 1.0, v67
	v_mul_f32_e32 v71, v66, v67
	v_bfi_b32 v66, s10, v92, v77
	v_mul_f32_e32 v69, 0.5, v69
	v_lshlrev_b32_e32 v70, 4, v80
	v_add_f32_e32 v66, 1.0, v66
	v_mul_f32_e32 v69, v69, v66
	v_or_b32_e32 v66, v70, v136
	v_ashrrev_i32_e32 v67, 31, v66
	v_lshlrev_b64 v[66:67], 10, v[66:67]
	v_lshl_add_u64 v[72:73], v[134:135], 0, v[66:67]
	v_cvt_pk_bf16_f32 v66, v74, v71
	v_cvt_pk_bf16_f32 v67, v87, v75
	v_cvt_pk_bf16_f32 v68, v76, v68
	v_cvt_pk_bf16_f32 v69, v88, v69
	global_store_dwordx4 v[72:73], v[66:69], off
	s_nop 1
	v_mov_b64_e32 v[66:67], v[220:221]
	v_mov_b64_e32 v[68:69], v[222:223]
	s_waitcnt vmcnt(14)
	v_lshlrev_b32_e32 v71, 16, v66
	v_fma_f32 v62, v38, v71, v62
	v_mul_f32_e32 v71, 0x3d372713, v62
	v_mul_f32_e32 v71, v62, v71
	v_fma_f32 v71, v62, v71, v62
	v_mul_f32_e32 v71, 0x3f4c422a, v71
	v_mul_f32_e64 v72, |v71|, s76
	v_add_f32_e32 v72, v72, v72
	v_exp_f32_e32 v72, v72
	s_nop 0
	v_add_f32_e32 v72, 1.0, v72
	v_rcp_f32_e32 v72, v72
	s_nop 0
	v_fma_f32 v72, v72, -2.0, 1.0
	v_lshlrev_b32_e32 v73, 16, v68
	v_fma_f32 v58, v26, v73, v58
	v_mul_f32_e32 v73, 0x3d372713, v58
	v_mul_f32_e32 v73, v58, v73
	v_fma_f32 v73, v58, v73, v58
	v_mul_f32_e32 v73, 0x3f4c422a, v73
	v_mul_f32_e64 v74, |v73|, s76
	v_add_f32_e32 v74, v74, v74
	v_exp_f32_e32 v74, v74
	s_nop 0
	v_add_f32_e32 v74, 1.0, v74
	v_rcp_f32_e32 v74, v74
	s_nop 0
	v_fma_f32 v74, v74, -2.0, 1.0
	v_and_b32_e32 v66, 0xffff0000, v66
	v_fma_f32 v66, v39, v66, v63
	v_mul_f32_e32 v63, 0x3d372713, v66
	v_mul_f32_e32 v63, v66, v63
	v_fma_f32 v63, v66, v63, v66
	v_mul_f32_e32 v63, 0x3f4c422a, v63
	v_mul_f32_e64 v75, |v63|, s76
	v_add_f32_e32 v75, v75, v75
	v_exp_f32_e32 v75, v75
	s_nop 0
	v_add_f32_e32 v75, 1.0, v75
	v_rcp_f32_e32 v75, v75
	s_nop 0
	v_fma_f32 v75, v75, -2.0, 1.0
	v_and_b32_e32 v68, 0xffff0000, v68
	v_fma_f32 v68, v27, v68, v59
	v_mul_f32_e32 v59, 0x3d372713, v68
	v_mul_f32_e32 v59, v68, v59
	v_fma_f32 v59, v68, v59, v68
	v_mul_f32_e32 v59, 0x3f4c422a, v59
	v_mul_f32_e64 v76, |v59|, s76
	v_add_f32_e32 v76, v76, v76
	v_exp_f32_e32 v76, v76
	s_nop 0
	v_add_f32_e32 v76, 1.0, v76
	v_rcp_f32_e32 v76, v76
	s_nop 0
	v_fma_f32 v76, v76, -2.0, 1.0
	v_lshlrev_b32_e32 v77, 16, v67
	v_fma_f32 v64, v40, v77, v64
	v_mul_f32_e32 v77, 0x3d372713, v64
	v_mul_f32_e32 v77, v64, v77
	v_fma_f32 v77, v64, v77, v64
	v_mul_f32_e32 v77, 0x3f4c422a, v77
	v_mul_f32_e64 v78, |v77|, s76
	v_add_f32_e32 v78, v78, v78
	v_exp_f32_e32 v78, v78
	s_nop 0
	v_add_f32_e32 v78, 1.0, v78
	v_rcp_f32_e32 v78, v78
	s_nop 0
	v_fma_f32 v78, v78, -2.0, 1.0
	v_lshlrev_b32_e32 v79, 16, v69
	v_fma_f32 v60, v28, v79, v60
	v_mul_f32_e32 v79, 0x3d372713, v60
	v_mul_f32_e32 v79, v60, v79
	v_fma_f32 v79, v60, v79, v60
	v_mul_f32_e32 v79, 0x3f4c422a, v79
	v_mul_f32_e64 v80, |v79|, s76
	v_add_f32_e32 v80, v80, v80
	v_exp_f32_e32 v80, v80
	s_nop 0
	v_add_f32_e32 v80, 1.0, v80
	v_rcp_f32_e32 v80, v80
	s_nop 0
	v_fma_f32 v80, v80, -2.0, 1.0
	v_and_b32_e32 v67, 0xffff0000, v67
	v_fmac_f32_e32 v65, v41, v67
	v_mul_f32_e32 v67, 0x3d372713, v65
	v_mul_f32_e32 v67, v65, v67
	v_fma_f32 v67, v65, v67, v65
	v_mul_f32_e32 v67, 0x3f4c422a, v67
	v_mul_f32_e64 v81, |v67|, s76
	v_add_f32_e32 v81, v81, v81
	v_exp_f32_e32 v81, v81
	s_nop 0
	v_add_f32_e32 v81, 1.0, v81
	v_rcp_f32_e32 v81, v81
	s_nop 0
	v_fma_f32 v81, v81, -2.0, 1.0
	v_and_b32_e32 v69, 0xffff0000, v69
	v_fmac_f32_e32 v61, v29, v69
	v_mul_f32_e32 v69, 0x3d372713, v61
	v_mul_f32_e32 v69, v61, v69
	v_fma_f32 v69, v61, v69, v61
	v_mul_f32_e32 v69, 0x3f4c422a, v69
	v_mul_f32_e64 v82, |v69|, s76
	v_add_f32_e32 v82, v82, v82
	v_exp_f32_e32 v82, v82
	s_nop 0
	v_add_f32_e32 v82, 1.0, v82
	v_rcp_f32_e32 v82, v82
	s_nop 0
	v_fma_f32 v82, v82, -2.0, 1.0
	v_bfi_b32 v67, s10, v81, v67
	v_mul_f32_e32 v65, 0.5, v65
	v_add_f32_e32 v67, 1.0, v67
	v_mul_f32_e32 v65, v65, v67
	v_bfi_b32 v67, s10, v80, v79
	v_mul_f32_e32 v60, 0.5, v60
	v_add_f32_e32 v67, 1.0, v67
	v_mul_f32_e32 v67, v60, v67
	v_mul_f32_e32 v60, 0.5, v68
	v_bfi_b32 v68, s10, v74, v73
	v_mul_f32_e32 v58, 0.5, v58
	v_add_f32_e32 v68, 1.0, v68
	v_mul_f32_e32 v68, v58, v68
	v_bfi_b32 v58, s10, v76, v59
	v_mul_f32_e32 v59, 0.5, v62
	v_bfi_b32 v62, s10, v72, v71
	v_add_f32_e32 v58, 1.0, v58
	v_add_f32_e32 v62, 1.0, v62
	v_mul_f32_e32 v60, v60, v58
	v_mul_f32_e32 v58, 0.5, v66
	v_mul_f32_e32 v66, v59, v62
	v_bfi_b32 v59, s10, v75, v63
	v_add_f32_e32 v59, 1.0, v59
	v_mul_f32_e32 v71, v58, v59
	v_bfi_b32 v58, s10, v82, v69
	v_mul_f32_e32 v61, 0.5, v61
	v_add_f32_e32 v58, 1.0, v58
	v_bfi_b32 v77, s10, v78, v77
	v_mul_f32_e32 v61, v61, v58
	v_or_b32_e32 v58, v70, v130
	v_mul_f32_e32 v64, 0.5, v64
	v_add_f32_e32 v77, 1.0, v77
	v_ashrrev_i32_e32 v59, 31, v58
	v_mul_f32_e32 v64, v64, v77
	v_lshlrev_b64 v[58:59], 10, v[58:59]
	v_lshl_add_u64 v[62:63], v[134:135], 0, v[58:59]
	v_cvt_pk_bf16_f32 v59, v64, v65
	v_add_u32_e32 v64, 0x90, v142
	v_cvt_pk_bf16_f32 v58, v66, v71
	v_cvt_pk_bf16_f32 v60, v68, v60
	v_cvt_pk_bf16_f32 v61, v67, v61
	v_ashrrev_i32_e32 v65, 31, v64
	global_store_dwordx4 v[62:63], v[58:61], off
	s_nop 1
	v_lshlrev_b64 v[58:59], 9, v[64:65]
	v_lshl_add_u64 v[58:59], s[0:1], 0, v[58:59]
	v_lshl_add_u64 v[62:63], v[58:59], 0, v[0:1]
	s_nop 1
	v_mov_b64_e32 v[58:59], v[224:225]
	v_mov_b64_e32 v[60:61], v[226:227]
	s_waitcnt vmcnt(14)
	v_lshlrev_b32_e32 v65, 16, v58
	v_fma_f32 v54, v38, v65, v54
	v_mul_f32_e32 v65, 0x3d372713, v54
	v_mul_f32_e32 v65, v54, v65
	v_fma_f32 v65, v54, v65, v54
	v_mul_f32_e32 v65, 0x3f4c422a, v65
	v_mul_f32_e64 v66, |v65|, s76
	v_add_f32_e32 v66, v66, v66
	v_exp_f32_e32 v66, v66
	s_nop 0
	v_add_f32_e32 v66, 1.0, v66
	v_rcp_f32_e32 v66, v66
	s_nop 0
	v_fma_f32 v66, v66, -2.0, 1.0
	v_lshlrev_b32_e32 v67, 16, v60
	v_fma_f32 v50, v26, v67, v50
	v_mul_f32_e32 v67, 0x3d372713, v50
	v_mul_f32_e32 v67, v50, v67
	v_fma_f32 v67, v50, v67, v50
	v_mul_f32_e32 v67, 0x3f4c422a, v67
	v_mul_f32_e64 v68, |v67|, s76
	v_add_f32_e32 v68, v68, v68
	v_exp_f32_e32 v68, v68
	s_nop 0
	v_add_f32_e32 v68, 1.0, v68
	v_rcp_f32_e32 v68, v68
	s_nop 0
	v_fma_f32 v68, v68, -2.0, 1.0
	v_and_b32_e32 v58, 0xffff0000, v58
	v_fma_f32 v58, v39, v58, v55
	v_mul_f32_e32 v55, 0x3d372713, v58
	v_mul_f32_e32 v55, v58, v55
	v_fma_f32 v55, v58, v55, v58
	v_mul_f32_e32 v55, 0x3f4c422a, v55
	v_mul_f32_e64 v69, |v55|, s76
	v_add_f32_e32 v69, v69, v69
	v_exp_f32_e32 v69, v69
	s_nop 0
	v_add_f32_e32 v69, 1.0, v69
	v_rcp_f32_e32 v69, v69
	s_nop 0
	v_fma_f32 v69, v69, -2.0, 1.0
	v_and_b32_e32 v60, 0xffff0000, v60
	v_fma_f32 v60, v27, v60, v51
	v_mul_f32_e32 v51, 0x3d372713, v60
	v_mul_f32_e32 v51, v60, v51
	v_fma_f32 v51, v60, v51, v60
	v_mul_f32_e32 v51, 0x3f4c422a, v51
	v_mul_f32_e64 v70, |v51|, s76
	v_add_f32_e32 v70, v70, v70
	v_exp_f32_e32 v70, v70
	s_nop 0
	v_add_f32_e32 v70, 1.0, v70
	v_rcp_f32_e32 v70, v70
	s_nop 0
	v_fma_f32 v70, v70, -2.0, 1.0
	v_lshlrev_b32_e32 v71, 16, v59
	v_fma_f32 v56, v40, v71, v56
	v_mul_f32_e32 v71, 0x3d372713, v56
	v_mul_f32_e32 v71, v56, v71
	v_fma_f32 v71, v56, v71, v56
	v_mul_f32_e32 v71, 0x3f4c422a, v71
	v_mul_f32_e64 v72, |v71|, s76
	v_add_f32_e32 v72, v72, v72
	v_exp_f32_e32 v72, v72
	s_nop 0
	v_add_f32_e32 v72, 1.0, v72
	v_rcp_f32_e32 v72, v72
	s_nop 0
	v_fma_f32 v72, v72, -2.0, 1.0
	v_lshlrev_b32_e32 v73, 16, v61
	v_fma_f32 v52, v28, v73, v52
	v_mul_f32_e32 v73, 0x3d372713, v52
	v_mul_f32_e32 v73, v52, v73
	v_fma_f32 v73, v52, v73, v52
	v_mul_f32_e32 v73, 0x3f4c422a, v73
	v_mul_f32_e64 v74, |v73|, s76
	v_add_f32_e32 v74, v74, v74
	v_exp_f32_e32 v74, v74
	s_nop 0
	v_add_f32_e32 v74, 1.0, v74
	v_rcp_f32_e32 v74, v74
	s_nop 0
	v_fma_f32 v74, v74, -2.0, 1.0
	v_and_b32_e32 v59, 0xffff0000, v59
	v_fmac_f32_e32 v57, v41, v59
	v_mul_f32_e32 v59, 0x3d372713, v57
	v_mul_f32_e32 v59, v57, v59
	v_fma_f32 v59, v57, v59, v57
	v_mul_f32_e32 v59, 0x3f4c422a, v59
	v_mul_f32_e64 v75, |v59|, s76
	v_add_f32_e32 v75, v75, v75
	v_exp_f32_e32 v75, v75
	s_nop 0
	v_add_f32_e32 v75, 1.0, v75
	v_rcp_f32_e32 v75, v75
	s_nop 0
	v_fma_f32 v75, v75, -2.0, 1.0
	v_and_b32_e32 v61, 0xffff0000, v61
	v_fmac_f32_e32 v53, v29, v61
	v_mul_f32_e32 v61, 0x3d372713, v53
	v_mul_f32_e32 v61, v53, v61
	v_fma_f32 v61, v53, v61, v53
	v_mul_f32_e32 v61, 0x3f4c422a, v61
	v_mul_f32_e64 v76, |v61|, s76
	v_add_f32_e32 v76, v76, v76
	v_exp_f32_e32 v76, v76
	s_nop 0
	v_add_f32_e32 v76, 1.0, v76
	v_rcp_f32_e32 v76, v76
	s_nop 0
	v_fma_f32 v76, v76, -2.0, 1.0
	v_bfi_b32 v71, s10, v72, v71
	v_mul_f32_e32 v56, 0.5, v56
	v_add_f32_e32 v71, 1.0, v71
	v_mul_f32_e32 v71, v56, v71
	v_bfi_b32 v56, s10, v75, v59
	v_mul_f32_e32 v57, 0.5, v57
	v_add_f32_e32 v56, 1.0, v56
	v_mul_f32_e32 v59, v57, v56
	v_bfi_b32 v56, s10, v74, v73
	v_mul_f32_e32 v52, 0.5, v52
	v_add_f32_e32 v56, 1.0, v56
	v_mul_f32_e32 v72, v52, v56
	v_bfi_b32 v56, s10, v68, v67
	v_mul_f32_e32 v50, 0.5, v50
	v_add_f32_e32 v56, 1.0, v56
	v_mul_f32_e32 v52, 0.5, v60
	v_mul_f32_e32 v60, v50, v56
	v_bfi_b32 v50, s10, v70, v51
	v_mul_f32_e32 v51, 0.5, v54
	v_bfi_b32 v54, s10, v66, v65
	v_add_f32_e32 v50, 1.0, v50
	v_add_f32_e32 v54, 1.0, v54
	v_mul_f32_e32 v52, v52, v50
	v_mul_f32_e32 v50, 0.5, v58
	v_mul_f32_e32 v58, v51, v54
	v_bfi_b32 v51, s10, v69, v55
	v_add_f32_e32 v51, 1.0, v51
	v_mul_f32_e32 v55, v50, v51
	v_bfi_b32 v50, s10, v76, v61
	v_mul_f32_e32 v53, 0.5, v53
	v_lshlrev_b32_e32 v54, 4, v64
	v_add_f32_e32 v50, 1.0, v50
	v_mul_f32_e32 v53, v53, v50
	v_or_b32_e32 v50, v54, v136
	v_ashrrev_i32_e32 v51, 31, v50
	v_lshlrev_b64 v[50:51], 10, v[50:51]
	v_lshl_add_u64 v[56:57], v[134:135], 0, v[50:51]
	v_cvt_pk_bf16_f32 v50, v58, v55
	v_cvt_pk_bf16_f32 v51, v71, v59
	v_cvt_pk_bf16_f32 v52, v60, v52
	v_cvt_pk_bf16_f32 v53, v72, v53
	global_store_dwordx4 v[56:57], v[50:53], off
	s_nop 1
	v_mov_b64_e32 v[50:51], v[228:229]
	v_mov_b64_e32 v[52:53], v[230:231]
	s_waitcnt vmcnt(14)
	v_lshlrev_b32_e32 v55, 16, v50
	v_fma_f32 v46, v38, v55, v46
	v_mul_f32_e32 v55, 0x3d372713, v46
	v_mul_f32_e32 v55, v46, v55
	v_fma_f32 v55, v46, v55, v46
	v_mul_f32_e32 v55, 0x3f4c422a, v55
	v_mul_f32_e64 v56, |v55|, s76
	v_add_f32_e32 v56, v56, v56
	v_exp_f32_e32 v56, v56
	s_nop 0
	v_add_f32_e32 v56, 1.0, v56
	v_rcp_f32_e32 v56, v56
	s_nop 0
	v_fma_f32 v56, v56, -2.0, 1.0
	v_lshlrev_b32_e32 v57, 16, v52
	v_fma_f32 v42, v26, v57, v42
	v_mul_f32_e32 v57, 0x3d372713, v42
	v_mul_f32_e32 v57, v42, v57
	v_fma_f32 v57, v42, v57, v42
	v_mul_f32_e32 v57, 0x3f4c422a, v57
	v_mul_f32_e64 v58, |v57|, s76
	v_add_f32_e32 v58, v58, v58
	v_exp_f32_e32 v58, v58
	s_nop 0
	v_add_f32_e32 v58, 1.0, v58
	v_rcp_f32_e32 v58, v58
	s_nop 0
	v_fma_f32 v58, v58, -2.0, 1.0
	v_and_b32_e32 v50, 0xffff0000, v50
	v_fma_f32 v50, v39, v50, v47
	v_mul_f32_e32 v47, 0x3d372713, v50
	v_mul_f32_e32 v47, v50, v47
	v_fma_f32 v47, v50, v47, v50
	v_mul_f32_e32 v47, 0x3f4c422a, v47
	v_mul_f32_e64 v59, |v47|, s76
	v_add_f32_e32 v59, v59, v59
	v_exp_f32_e32 v59, v59
	s_nop 0
	v_add_f32_e32 v59, 1.0, v59
	v_rcp_f32_e32 v59, v59
	s_nop 0
	v_fma_f32 v59, v59, -2.0, 1.0
	v_and_b32_e32 v52, 0xffff0000, v52
	v_fma_f32 v52, v27, v52, v43
	v_mul_f32_e32 v43, 0x3d372713, v52
	v_mul_f32_e32 v43, v52, v43
	v_fma_f32 v43, v52, v43, v52
	v_mul_f32_e32 v43, 0x3f4c422a, v43
	v_mul_f32_e64 v60, |v43|, s76
	v_add_f32_e32 v60, v60, v60
	v_exp_f32_e32 v60, v60
	s_nop 0
	v_add_f32_e32 v60, 1.0, v60
	v_rcp_f32_e32 v60, v60
	s_nop 0
	v_fma_f32 v60, v60, -2.0, 1.0
	v_lshlrev_b32_e32 v61, 16, v51
	v_fma_f32 v48, v40, v61, v48
	v_mul_f32_e32 v61, 0x3d372713, v48
	v_mul_f32_e32 v61, v48, v61
	v_fma_f32 v61, v48, v61, v48
	v_mul_f32_e32 v61, 0x3f4c422a, v61
	v_mul_f32_e64 v62, |v61|, s76
	v_add_f32_e32 v62, v62, v62
	v_exp_f32_e32 v62, v62
	s_nop 0
	v_add_f32_e32 v62, 1.0, v62
	v_rcp_f32_e32 v62, v62
	s_nop 0
	v_fma_f32 v62, v62, -2.0, 1.0
	v_lshlrev_b32_e32 v63, 16, v53
	v_fma_f32 v44, v28, v63, v44
	v_mul_f32_e32 v63, 0x3d372713, v44
	v_mul_f32_e32 v63, v44, v63
	v_fma_f32 v63, v44, v63, v44
	v_mul_f32_e32 v63, 0x3f4c422a, v63
	v_mul_f32_e64 v64, |v63|, s76
	v_add_f32_e32 v64, v64, v64
	v_exp_f32_e32 v64, v64
	s_nop 0
	v_add_f32_e32 v64, 1.0, v64
	v_rcp_f32_e32 v64, v64
	s_nop 0
	v_fma_f32 v64, v64, -2.0, 1.0
	v_and_b32_e32 v51, 0xffff0000, v51
	v_fmac_f32_e32 v49, v41, v51
	v_mul_f32_e32 v51, 0x3d372713, v49
	v_mul_f32_e32 v51, v49, v51
	v_fma_f32 v51, v49, v51, v49
	v_mul_f32_e32 v51, 0x3f4c422a, v51
	v_mul_f32_e64 v65, |v51|, s76
	v_add_f32_e32 v65, v65, v65
	v_exp_f32_e32 v65, v65
	s_nop 0
	v_add_f32_e32 v65, 1.0, v65
	v_rcp_f32_e32 v65, v65
	s_nop 0
	v_fma_f32 v65, v65, -2.0, 1.0
	v_and_b32_e32 v53, 0xffff0000, v53
	v_fmac_f32_e32 v45, v29, v53
	v_mul_f32_e32 v53, 0x3d372713, v45
	v_mul_f32_e32 v53, v45, v53
	v_fma_f32 v53, v45, v53, v45
	v_mul_f32_e32 v53, 0x3f4c422a, v53
	v_mul_f32_e64 v66, |v53|, s76
	v_add_f32_e32 v66, v66, v66
	v_exp_f32_e32 v66, v66
	s_nop 0
	v_add_f32_e32 v66, 1.0, v66
	v_rcp_f32_e32 v66, v66
	s_nop 0
	v_fma_f32 v66, v66, -2.0, 1.0
	v_bfi_b32 v51, s10, v65, v51
	v_mul_f32_e32 v49, 0.5, v49
	v_add_f32_e32 v51, 1.0, v51
	v_mul_f32_e32 v49, v49, v51
	v_bfi_b32 v51, s10, v64, v63
	v_mul_f32_e32 v44, 0.5, v44
	v_add_f32_e32 v51, 1.0, v51
	v_mul_f32_e32 v51, v44, v51
	v_mul_f32_e32 v44, 0.5, v52
	v_bfi_b32 v52, s10, v58, v57
	v_mul_f32_e32 v42, 0.5, v42
	v_add_f32_e32 v52, 1.0, v52
	v_mul_f32_e32 v52, v42, v52
	v_bfi_b32 v42, s10, v60, v43
	v_mul_f32_e32 v43, 0.5, v46
	v_bfi_b32 v46, s10, v56, v55
	v_add_f32_e32 v42, 1.0, v42
	v_add_f32_e32 v46, 1.0, v46
	v_mul_f32_e32 v44, v44, v42
	v_mul_f32_e32 v42, 0.5, v50
	v_mul_f32_e32 v50, v43, v46
	v_bfi_b32 v43, s10, v59, v47
	v_add_f32_e32 v43, 1.0, v43
	v_mul_f32_e32 v55, v42, v43
	v_bfi_b32 v42, s10, v66, v53
	v_mul_f32_e32 v45, 0.5, v45
	v_add_f32_e32 v42, 1.0, v42
	v_bfi_b32 v61, s10, v62, v61
	v_mul_f32_e32 v45, v45, v42
	v_or_b32_e32 v42, v54, v130
	v_mul_f32_e32 v48, 0.5, v48
	v_add_f32_e32 v61, 1.0, v61
	v_ashrrev_i32_e32 v43, 31, v42
	v_mul_f32_e32 v48, v48, v61
	v_lshlrev_b64 v[42:43], 10, v[42:43]
	v_lshl_add_u64 v[46:47], v[134:135], 0, v[42:43]
	v_cvt_pk_bf16_f32 v43, v48, v49
	v_add_u32_e32 v48, 0xa0, v142
	v_cvt_pk_bf16_f32 v42, v50, v55
	v_cvt_pk_bf16_f32 v44, v52, v44
	v_cvt_pk_bf16_f32 v45, v51, v45
	v_ashrrev_i32_e32 v49, 31, v48
	global_store_dwordx4 v[46:47], v[42:45], off
	s_nop 1
	v_lshlrev_b64 v[42:43], 9, v[48:49]
	v_lshl_add_u64 v[42:43], s[0:1], 0, v[42:43]
	v_lshl_add_u64 v[46:47], v[42:43], 0, v[0:1]
	s_nop 1
	v_mov_b64_e32 v[42:43], v[232:233]
	v_mov_b64_e32 v[44:45], v[234:235]
	s_waitcnt vmcnt(14)
	v_lshlrev_b32_e32 v49, 16, v42
	v_fma_f32 v34, v38, v49, v34
	v_mul_f32_e32 v49, 0x3d372713, v34
	v_mul_f32_e32 v49, v34, v49
	v_fma_f32 v49, v34, v49, v34
	v_mul_f32_e32 v49, 0x3f4c422a, v49
	v_mul_f32_e64 v50, |v49|, s76
	v_add_f32_e32 v50, v50, v50
	v_exp_f32_e32 v50, v50
	s_nop 0
	v_add_f32_e32 v50, 1.0, v50
	v_rcp_f32_e32 v50, v50
	s_nop 0
	v_fma_f32 v50, v50, -2.0, 1.0
	v_lshlrev_b32_e32 v51, 16, v44
	v_fma_f32 v30, v26, v51, v30
	v_mul_f32_e32 v51, 0x3d372713, v30
	v_mul_f32_e32 v51, v30, v51
	v_fma_f32 v51, v30, v51, v30
	v_mul_f32_e32 v51, 0x3f4c422a, v51
	v_mul_f32_e64 v52, |v51|, s76
	v_add_f32_e32 v52, v52, v52
	v_exp_f32_e32 v52, v52
	s_nop 0
	v_add_f32_e32 v52, 1.0, v52
	v_rcp_f32_e32 v52, v52
	s_nop 0
	v_fma_f32 v52, v52, -2.0, 1.0
	v_and_b32_e32 v42, 0xffff0000, v42
	v_fma_f32 v42, v39, v42, v35
	v_mul_f32_e32 v35, 0x3d372713, v42
	v_mul_f32_e32 v35, v42, v35
	v_fma_f32 v35, v42, v35, v42
	v_mul_f32_e32 v35, 0x3f4c422a, v35
	v_mul_f32_e64 v53, |v35|, s76
	v_add_f32_e32 v53, v53, v53
	v_exp_f32_e32 v53, v53
	s_nop 0
	v_add_f32_e32 v53, 1.0, v53
	v_rcp_f32_e32 v53, v53
	s_nop 0
	v_fma_f32 v53, v53, -2.0, 1.0
	v_and_b32_e32 v44, 0xffff0000, v44
	v_fma_f32 v44, v27, v44, v31
	v_mul_f32_e32 v31, 0x3d372713, v44
	v_mul_f32_e32 v31, v44, v31
	v_fma_f32 v31, v44, v31, v44
	v_mul_f32_e32 v31, 0x3f4c422a, v31
	v_mul_f32_e64 v54, |v31|, s76
	v_add_f32_e32 v54, v54, v54
	v_exp_f32_e32 v54, v54
	s_nop 0
	v_add_f32_e32 v54, 1.0, v54
	v_rcp_f32_e32 v54, v54
	s_nop 0
	v_fma_f32 v54, v54, -2.0, 1.0
	v_lshlrev_b32_e32 v55, 16, v43
	v_fma_f32 v36, v40, v55, v36
	v_mul_f32_e32 v55, 0x3d372713, v36
	v_mul_f32_e32 v55, v36, v55
	v_fma_f32 v55, v36, v55, v36
	v_mul_f32_e32 v55, 0x3f4c422a, v55
	v_mul_f32_e64 v56, |v55|, s76
	v_add_f32_e32 v56, v56, v56
	v_exp_f32_e32 v56, v56
	s_nop 0
	v_add_f32_e32 v56, 1.0, v56
	v_rcp_f32_e32 v56, v56
	s_nop 0
	v_fma_f32 v56, v56, -2.0, 1.0
	v_lshlrev_b32_e32 v57, 16, v45
	v_fma_f32 v32, v28, v57, v32
	v_mul_f32_e32 v57, 0x3d372713, v32
	v_mul_f32_e32 v57, v32, v57
	v_fma_f32 v57, v32, v57, v32
	v_mul_f32_e32 v57, 0x3f4c422a, v57
	v_mul_f32_e64 v58, |v57|, s76
	v_add_f32_e32 v58, v58, v58
	v_exp_f32_e32 v58, v58
	s_nop 0
	v_add_f32_e32 v58, 1.0, v58
	v_rcp_f32_e32 v58, v58
	s_nop 0
	v_fma_f32 v58, v58, -2.0, 1.0
	v_and_b32_e32 v43, 0xffff0000, v43
	v_fmac_f32_e32 v37, v41, v43
	v_mul_f32_e32 v43, 0x3d372713, v37
	v_mul_f32_e32 v43, v37, v43
	v_fma_f32 v43, v37, v43, v37
	v_mul_f32_e32 v43, 0x3f4c422a, v43
	v_mul_f32_e64 v59, |v43|, s76
	v_add_f32_e32 v59, v59, v59
	v_exp_f32_e32 v59, v59
	s_nop 0
	v_add_f32_e32 v59, 1.0, v59
	v_rcp_f32_e32 v59, v59
	s_nop 0
	v_fma_f32 v59, v59, -2.0, 1.0
	v_and_b32_e32 v45, 0xffff0000, v45
	v_fmac_f32_e32 v33, v29, v45
	v_mul_f32_e32 v45, 0x3d372713, v33
	v_mul_f32_e32 v45, v33, v45
	v_fma_f32 v45, v33, v45, v33
	v_mul_f32_e32 v45, 0x3f4c422a, v45
	v_mul_f32_e64 v60, |v45|, s76
	v_add_f32_e32 v60, v60, v60
	v_exp_f32_e32 v60, v60
	s_nop 0
	v_add_f32_e32 v60, 1.0, v60
	v_rcp_f32_e32 v60, v60
	s_nop 0
	v_fma_f32 v60, v60, -2.0, 1.0
	v_bfi_b32 v55, s10, v56, v55
	v_mul_f32_e32 v36, 0.5, v36
	v_add_f32_e32 v55, 1.0, v55
	v_mul_f32_e32 v55, v36, v55
	v_bfi_b32 v36, s10, v59, v43
	v_mul_f32_e32 v37, 0.5, v37
	v_add_f32_e32 v36, 1.0, v36
	v_mul_f32_e32 v43, v37, v36
	v_bfi_b32 v36, s10, v58, v57
	v_mul_f32_e32 v32, 0.5, v32
	v_add_f32_e32 v36, 1.0, v36
	v_mul_f32_e32 v56, v32, v36
	v_bfi_b32 v36, s10, v52, v51
	v_mul_f32_e32 v30, 0.5, v30
	v_add_f32_e32 v36, 1.0, v36
	v_mul_f32_e32 v32, 0.5, v44
	v_mul_f32_e32 v44, v30, v36
	v_bfi_b32 v30, s10, v54, v31
	v_mul_f32_e32 v31, 0.5, v34
	v_bfi_b32 v34, s10, v50, v49
	v_add_f32_e32 v30, 1.0, v30
	v_add_f32_e32 v34, 1.0, v34
	v_mul_f32_e32 v32, v32, v30
	v_mul_f32_e32 v30, 0.5, v42
	v_mul_f32_e32 v42, v31, v34
	v_bfi_b32 v31, s10, v53, v35
	v_add_f32_e32 v31, 1.0, v31
	v_mul_f32_e32 v35, v30, v31
	v_bfi_b32 v30, s10, v60, v45
	v_mul_f32_e32 v33, 0.5, v33
	v_lshlrev_b32_e32 v34, 4, v48
	v_add_f32_e32 v30, 1.0, v30
	v_mul_f32_e32 v33, v33, v30
	v_or_b32_e32 v30, v34, v136
	v_ashrrev_i32_e32 v31, 31, v30
	v_lshlrev_b64 v[30:31], 10, v[30:31]
	v_lshl_add_u64 v[36:37], v[134:135], 0, v[30:31]
	v_cvt_pk_bf16_f32 v30, v42, v35
	v_cvt_pk_bf16_f32 v31, v55, v43
	v_cvt_pk_bf16_f32 v32, v44, v32
	v_cvt_pk_bf16_f32 v33, v56, v33
	global_store_dwordx4 v[36:37], v[30:33], off
	s_nop 1
	v_mov_b64_e32 v[30:31], v[236:237]
	v_mov_b64_e32 v[32:33], v[238:239]
	s_waitcnt vmcnt(14)
	v_lshlrev_b32_e32 v35, 16, v30
	v_fma_f32 v22, v38, v35, v22
	v_mul_f32_e32 v35, 0x3d372713, v22
	v_mul_f32_e32 v35, v22, v35
	v_fma_f32 v35, v22, v35, v22
	v_mul_f32_e32 v35, 0x3f4c422a, v35
	v_mul_f32_e64 v36, |v35|, s76
	v_add_f32_e32 v36, v36, v36
	v_exp_f32_e32 v36, v36
	s_nop 0
	v_add_f32_e32 v36, 1.0, v36
	v_rcp_f32_e32 v36, v36
	s_nop 0
	v_fma_f32 v36, v36, -2.0, 1.0
	v_lshlrev_b32_e32 v37, 16, v32
	v_fma_f32 v18, v26, v37, v18
	v_mul_f32_e32 v37, 0x3d372713, v18
	v_mul_f32_e32 v37, v18, v37
	v_fma_f32 v37, v18, v37, v18
	v_mul_f32_e32 v37, 0x3f4c422a, v37
	v_mul_f32_e64 v42, |v37|, s76
	v_add_f32_e32 v42, v42, v42
	v_exp_f32_e32 v42, v42
	s_nop 0
	v_add_f32_e32 v42, 1.0, v42
	v_rcp_f32_e32 v42, v42
	s_nop 0
	v_fma_f32 v42, v42, -2.0, 1.0
	v_and_b32_e32 v30, 0xffff0000, v30
	v_fma_f32 v30, v39, v30, v23
	v_mul_f32_e32 v23, 0x3d372713, v30
	v_mul_f32_e32 v23, v30, v23
	v_fma_f32 v23, v30, v23, v30
	v_mul_f32_e32 v23, 0x3f4c422a, v23
	v_mul_f32_e64 v43, |v23|, s76
	v_add_f32_e32 v43, v43, v43
	v_exp_f32_e32 v43, v43
	s_nop 0
	v_add_f32_e32 v43, 1.0, v43
	v_rcp_f32_e32 v43, v43
	s_nop 0
	v_fma_f32 v43, v43, -2.0, 1.0
	v_and_b32_e32 v32, 0xffff0000, v32
	v_fma_f32 v32, v27, v32, v19
	v_mul_f32_e32 v19, 0x3d372713, v32
	v_mul_f32_e32 v19, v32, v19
	v_fma_f32 v19, v32, v19, v32
	v_mul_f32_e32 v19, 0x3f4c422a, v19
	v_mul_f32_e64 v44, |v19|, s76
	v_add_f32_e32 v44, v44, v44
	v_exp_f32_e32 v44, v44
	s_nop 0
	v_add_f32_e32 v44, 1.0, v44
	v_rcp_f32_e32 v44, v44
	s_nop 0
	v_fma_f32 v44, v44, -2.0, 1.0
	v_lshlrev_b32_e32 v45, 16, v31
	v_fma_f32 v24, v40, v45, v24
	v_mul_f32_e32 v45, 0x3d372713, v24
	v_mul_f32_e32 v45, v24, v45
	v_fma_f32 v45, v24, v45, v24
	v_mul_f32_e32 v45, 0x3f4c422a, v45
	v_mul_f32_e64 v46, |v45|, s76
	v_add_f32_e32 v46, v46, v46
	v_exp_f32_e32 v46, v46
	s_nop 0
	v_add_f32_e32 v46, 1.0, v46
	v_rcp_f32_e32 v46, v46
	s_nop 0
	v_fma_f32 v46, v46, -2.0, 1.0
	v_lshlrev_b32_e32 v47, 16, v33
	v_fma_f32 v20, v28, v47, v20
	v_mul_f32_e32 v47, 0x3d372713, v20
	v_mul_f32_e32 v47, v20, v47
	v_fma_f32 v47, v20, v47, v20
	v_mul_f32_e32 v47, 0x3f4c422a, v47
	v_mul_f32_e64 v48, |v47|, s76
	v_add_f32_e32 v48, v48, v48
	v_exp_f32_e32 v48, v48
	s_nop 0
	v_add_f32_e32 v48, 1.0, v48
	v_rcp_f32_e32 v48, v48
	s_nop 0
	v_fma_f32 v48, v48, -2.0, 1.0
	v_and_b32_e32 v31, 0xffff0000, v31
	v_fmac_f32_e32 v25, v41, v31
	v_mul_f32_e32 v31, 0x3d372713, v25
	v_mul_f32_e32 v31, v25, v31
	v_fma_f32 v31, v25, v31, v25
	v_mul_f32_e32 v31, 0x3f4c422a, v31
	v_mul_f32_e64 v49, |v31|, s76
	v_add_f32_e32 v49, v49, v49
	v_exp_f32_e32 v49, v49
	s_nop 0
	v_add_f32_e32 v49, 1.0, v49
	v_rcp_f32_e32 v49, v49
	s_nop 0
	v_fma_f32 v49, v49, -2.0, 1.0
	v_and_b32_e32 v33, 0xffff0000, v33
	v_fmac_f32_e32 v21, v29, v33
	v_mul_f32_e32 v33, 0x3d372713, v21
	v_mul_f32_e32 v33, v21, v33
	v_fma_f32 v33, v21, v33, v21
	v_mul_f32_e32 v33, 0x3f4c422a, v33
	v_mul_f32_e64 v50, |v33|, s76
	v_add_f32_e32 v50, v50, v50
	v_exp_f32_e32 v50, v50
	s_nop 0
	v_add_f32_e32 v50, 1.0, v50
	v_rcp_f32_e32 v50, v50
	s_nop 0
	v_fma_f32 v50, v50, -2.0, 1.0
	v_bfi_b32 v31, s10, v49, v31
	v_mul_f32_e32 v25, 0.5, v25
	v_add_f32_e32 v31, 1.0, v31
	v_mul_f32_e32 v25, v25, v31
	v_bfi_b32 v31, s10, v48, v47
	v_mul_f32_e32 v20, 0.5, v20
	v_add_f32_e32 v31, 1.0, v31
	v_mul_f32_e32 v31, v20, v31
	v_mul_f32_e32 v20, 0.5, v32
	v_bfi_b32 v32, s10, v42, v37
	v_mul_f32_e32 v18, 0.5, v18
	v_add_f32_e32 v32, 1.0, v32
	v_mul_f32_e32 v32, v18, v32
	v_bfi_b32 v18, s10, v44, v19
	v_mul_f32_e32 v19, 0.5, v22
	v_bfi_b32 v22, s10, v36, v35
	v_add_f32_e32 v18, 1.0, v18
	v_add_f32_e32 v22, 1.0, v22
	v_mul_f32_e32 v20, v20, v18
	v_mul_f32_e32 v18, 0.5, v30
	v_mul_f32_e32 v30, v19, v22
	v_bfi_b32 v19, s10, v43, v23
	v_add_f32_e32 v19, 1.0, v19
	v_mul_f32_e32 v35, v18, v19
	v_bfi_b32 v18, s10, v50, v33
	v_mul_f32_e32 v21, 0.5, v21
	v_add_f32_e32 v18, 1.0, v18
	v_bfi_b32 v45, s10, v46, v45
	v_mul_f32_e32 v21, v21, v18
	v_or_b32_e32 v18, v34, v130
	v_mul_f32_e32 v24, 0.5, v24
	v_add_f32_e32 v45, 1.0, v45
	v_ashrrev_i32_e32 v19, 31, v18
	v_mul_f32_e32 v24, v24, v45
	v_lshlrev_b64 v[18:19], 10, v[18:19]
	v_lshl_add_u64 v[22:23], v[134:135], 0, v[18:19]
	v_cvt_pk_bf16_f32 v19, v24, v25
	v_add_u32_e32 v24, 0xb0, v142
	v_cvt_pk_bf16_f32 v18, v30, v35
	v_cvt_pk_bf16_f32 v20, v32, v20
	v_cvt_pk_bf16_f32 v21, v31, v21
	v_ashrrev_i32_e32 v25, 31, v24
	global_store_dwordx4 v[22:23], v[18:21], off
	s_nop 1
	v_lshlrev_b64 v[18:19], 9, v[24:25]
	v_lshl_add_u64 v[18:19], s[0:1], 0, v[18:19]
	v_lshl_add_u64 v[22:23], v[18:19], 0, v[0:1]
	s_nop 1
	v_mov_b64_e32 v[18:19], v[240:241]
	v_mov_b64_e32 v[20:21], v[242:243]
	s_waitcnt vmcnt(14)
	v_lshlrev_b32_e32 v0, 16, v18
	v_fma_f32 v0, v38, v0, v14
	v_mul_f32_e32 v14, 0x3d372713, v0
	v_mul_f32_e32 v14, v0, v14
	v_fma_f32 v14, v0, v14, v0
	v_mul_f32_e32 v14, 0x3f4c422a, v14
	v_mul_f32_e64 v25, |v14|, s76
	v_add_f32_e32 v25, v25, v25
	v_exp_f32_e32 v25, v25
	s_nop 0
	v_add_f32_e32 v25, 1.0, v25
	v_rcp_f32_e32 v25, v25
	s_nop 0
	v_fma_f32 v25, v25, -2.0, 1.0
	v_lshlrev_b32_e32 v30, 16, v20
	v_fma_f32 v10, v26, v30, v10
	v_mul_f32_e32 v30, 0x3d372713, v10
	v_mul_f32_e32 v30, v10, v30
	v_fma_f32 v30, v10, v30, v10
	v_mul_f32_e32 v30, 0x3f4c422a, v30
	v_mul_f32_e64 v31, |v30|, s76
	v_add_f32_e32 v31, v31, v31
	v_exp_f32_e32 v31, v31
	s_nop 0
	v_add_f32_e32 v31, 1.0, v31
	v_rcp_f32_e32 v31, v31
	s_nop 0
	v_fma_f32 v31, v31, -2.0, 1.0
	v_and_b32_e32 v18, 0xffff0000, v18
	v_fma_f32 v18, v39, v18, v15
	v_mul_f32_e32 v15, 0x3d372713, v18
	v_mul_f32_e32 v15, v18, v15
	v_fma_f32 v15, v18, v15, v18
	v_mul_f32_e32 v15, 0x3f4c422a, v15
	v_mul_f32_e64 v32, |v15|, s76
	v_add_f32_e32 v32, v32, v32
	v_exp_f32_e32 v32, v32
	s_nop 0
	v_add_f32_e32 v32, 1.0, v32
	v_rcp_f32_e32 v32, v32
	s_nop 0
	v_fma_f32 v32, v32, -2.0, 1.0
	v_and_b32_e32 v20, 0xffff0000, v20
	v_fma_f32 v20, v27, v20, v11
	v_mul_f32_e32 v11, 0x3d372713, v20
	v_mul_f32_e32 v11, v20, v11
	v_fma_f32 v11, v20, v11, v20
	v_mul_f32_e32 v11, 0x3f4c422a, v11
	v_mul_f32_e64 v33, |v11|, s76
	v_add_f32_e32 v33, v33, v33
	v_exp_f32_e32 v33, v33
	s_nop 0
	v_add_f32_e32 v33, 1.0, v33
	v_rcp_f32_e32 v33, v33
	s_nop 0
	v_fma_f32 v33, v33, -2.0, 1.0
	v_lshlrev_b32_e32 v34, 16, v19
	v_fma_f32 v16, v40, v34, v16
	v_mul_f32_e32 v34, 0x3d372713, v16
	v_mul_f32_e32 v34, v16, v34
	v_fma_f32 v34, v16, v34, v16
	v_mul_f32_e32 v34, 0x3f4c422a, v34
	v_mul_f32_e64 v35, |v34|, s76
	v_add_f32_e32 v35, v35, v35
	v_exp_f32_e32 v35, v35
	s_nop 0
	v_add_f32_e32 v35, 1.0, v35
	v_rcp_f32_e32 v35, v35
	s_nop 0
	v_fma_f32 v35, v35, -2.0, 1.0
	v_lshlrev_b32_e32 v36, 16, v21
	v_fma_f32 v12, v28, v36, v12
	v_mul_f32_e32 v36, 0x3d372713, v12
	v_mul_f32_e32 v36, v12, v36
	v_fma_f32 v36, v12, v36, v12
	v_mul_f32_e32 v36, 0x3f4c422a, v36
	v_mul_f32_e64 v37, |v36|, s76
	v_add_f32_e32 v37, v37, v37
	v_exp_f32_e32 v37, v37
	s_nop 0
	v_add_f32_e32 v37, 1.0, v37
	v_rcp_f32_e32 v37, v37
	s_nop 0
	v_fma_f32 v37, v37, -2.0, 1.0
	v_and_b32_e32 v19, 0xffff0000, v19
	v_fmac_f32_e32 v17, v41, v19
	v_mul_f32_e32 v19, 0x3d372713, v17
	v_mul_f32_e32 v19, v17, v19
	v_fma_f32 v19, v17, v19, v17
	v_mul_f32_e32 v19, 0x3f4c422a, v19
	v_mul_f32_e64 v42, |v19|, s76
	v_add_f32_e32 v42, v42, v42
	v_exp_f32_e32 v42, v42
	s_nop 0
	v_add_f32_e32 v42, 1.0, v42
	v_rcp_f32_e32 v42, v42
	s_nop 0
	v_fma_f32 v42, v42, -2.0, 1.0
	v_and_b32_e32 v21, 0xffff0000, v21
	v_fmac_f32_e32 v13, v29, v21
	v_mul_f32_e32 v21, 0x3d372713, v13
	v_mul_f32_e32 v21, v13, v21
	v_fma_f32 v21, v13, v21, v13
	v_mul_f32_e32 v21, 0x3f4c422a, v21
	v_mul_f32_e64 v43, |v21|, s76
	v_add_f32_e32 v43, v43, v43
	v_exp_f32_e32 v43, v43
	s_nop 0
	v_add_f32_e32 v43, 1.0, v43
	v_rcp_f32_e32 v43, v43
	s_nop 0
	v_fma_f32 v43, v43, -2.0, 1.0
	v_bfi_b32 v19, s10, v42, v19
	v_mul_f32_e32 v17, 0.5, v17
	v_add_f32_e32 v19, 1.0, v19
	v_mul_f32_e32 v17, v17, v19
	v_bfi_b32 v19, s10, v37, v36
	v_mul_f32_e32 v12, 0.5, v12
	v_add_f32_e32 v19, 1.0, v19
	v_mul_f32_e32 v19, v12, v19
	v_mul_f32_e32 v12, 0.5, v20
	v_bfi_b32 v20, s10, v31, v30
	v_mul_f32_e32 v10, 0.5, v10
	v_add_f32_e32 v20, 1.0, v20
	v_mul_f32_e32 v20, v10, v20
	v_bfi_b32 v10, s10, v33, v11
	v_bfi_b32 v11, s10, v25, v14
	v_add_f32_e32 v10, 1.0, v10
	v_mul_f32_e32 v0, 0.5, v0
	v_add_f32_e32 v11, 1.0, v11
	v_mul_f32_e32 v12, v12, v10
	v_mul_f32_e32 v10, 0.5, v18
	v_mul_f32_e32 v18, v0, v11
	v_bfi_b32 v0, s10, v32, v15
	v_add_f32_e32 v0, 1.0, v0
	v_mul_f32_e32 v25, v10, v0
	v_bfi_b32 v10, s10, v43, v21
	v_mul_f32_e32 v13, 0.5, v13
	v_lshlrev_b32_e32 v0, 4, v24
	v_add_f32_e32 v10, 1.0, v10
	v_bfi_b32 v34, s10, v35, v34
	v_mul_f32_e32 v13, v13, v10
	v_or_b32_e32 v10, v0, v136
	v_mul_f32_e32 v16, 0.5, v16
	v_add_f32_e32 v34, 1.0, v34
	v_ashrrev_i32_e32 v11, 31, v10
	v_mul_f32_e32 v16, v16, v34
	v_lshlrev_b64 v[10:11], 10, v[10:11]
	v_lshl_add_u64 v[14:15], v[134:135], 0, v[10:11]
	v_cvt_pk_bf16_f32 v10, v18, v25
	v_cvt_pk_bf16_f32 v11, v16, v17
	v_cvt_pk_bf16_f32 v12, v20, v12
	v_cvt_pk_bf16_f32 v13, v19, v13
	global_store_dwordx4 v[14:15], v[10:13], off
	global_load_dwordx4 v[10:13], v[22:23], off offset:256
	s_waitcnt vmcnt(0)
	v_lshlrev_b32_e32 v14, 16, v10
	v_and_b32_e32 v15, 0xffff0000, v10
	v_pk_fma_f32 v[6:7], v[38:39], v[14:15], v[6:7]
	s_nop 0
	v_mul_f32_e32 v10, 0x3d372713, v6
	v_mul_f32_e32 v10, v6, v10
	v_fma_f32 v10, v6, v10, v6
	v_mul_f32_e32 v10, 0x3f4c422a, v10
	v_mul_f32_e64 v14, |v10|, s76
	v_add_f32_e32 v14, v14, v14
	v_exp_f32_e32 v14, v14
	s_nop 0
	v_add_f32_e32 v14, 1.0, v14
	v_rcp_f32_e32 v14, v14
	s_nop 0
	v_fma_f32 v14, v14, -2.0, 1.0
	v_lshlrev_b32_e32 v16, 16, v12
	v_and_b32_e32 v17, 0xffff0000, v12
	v_pk_fma_f32 v[2:3], v[26:27], v[16:17], v[2:3]
	s_nop 0
	v_mul_f32_e32 v12, 0x3d372713, v2
	v_mul_f32_e32 v12, v2, v12
	v_fma_f32 v12, v2, v12, v2
	v_mul_f32_e32 v12, 0x3f4c422a, v12
	v_mul_f32_e64 v15, |v12|, s76
	v_add_f32_e32 v15, v15, v15
	v_exp_f32_e32 v15, v15
	s_nop 0
	v_add_f32_e32 v15, 1.0, v15
	v_rcp_f32_e32 v15, v15
	s_nop 0
	v_fma_f32 v15, v15, -2.0, 1.0
	v_mul_f32_e32 v16, 0x3d372713, v7
	v_mul_f32_e32 v16, v7, v16
	v_fma_f32 v16, v7, v16, v7
	v_mul_f32_e32 v16, 0x3f4c422a, v16
	v_mul_f32_e64 v17, |v16|, s76
	v_add_f32_e32 v17, v17, v17
	v_exp_f32_e32 v17, v17
	s_nop 0
	v_add_f32_e32 v17, 1.0, v17
	v_rcp_f32_e32 v17, v17
	s_nop 0
	v_fma_f32 v17, v17, -2.0, 1.0
	v_mul_f32_e32 v18, 0x3d372713, v3
	v_mul_f32_e32 v18, v3, v18
	v_fma_f32 v18, v3, v18, v3
	v_mul_f32_e32 v18, 0x3f4c422a, v18
	v_mul_f32_e64 v19, |v18|, s76
	v_add_f32_e32 v19, v19, v19
	v_exp_f32_e32 v19, v19
	s_nop 0
	v_add_f32_e32 v19, 1.0, v19
	v_rcp_f32_e32 v19, v19
	s_nop 0
	v_fma_f32 v19, v19, -2.0, 1.0
	v_lshlrev_b32_e32 v20, 16, v11
	v_and_b32_e32 v21, 0xffff0000, v11
	v_pk_fma_f32 v[8:9], v[40:41], v[20:21], v[8:9]
	s_nop 0
	v_mul_f32_e32 v11, 0x3d372713, v8
	v_mul_f32_e32 v11, v8, v11
	v_fma_f32 v11, v8, v11, v8
	v_mul_f32_e32 v11, 0x3f4c422a, v11
	v_mul_f32_e64 v20, |v11|, s76
	v_add_f32_e32 v20, v20, v20
	v_exp_f32_e32 v20, v20
	s_nop 0
	v_add_f32_e32 v20, 1.0, v20
	v_rcp_f32_e32 v20, v20
	s_nop 0
	v_fma_f32 v20, v20, -2.0, 1.0
	v_lshlrev_b32_e32 v22, 16, v13
	v_and_b32_e32 v23, 0xffff0000, v13
	v_pk_fma_f32 v[4:5], v[28:29], v[22:23], v[4:5]
	s_nop 0
	v_mul_f32_e32 v13, 0x3d372713, v4
	v_mul_f32_e32 v13, v4, v13
	v_fma_f32 v13, v4, v13, v4
	v_mul_f32_e32 v13, 0x3f4c422a, v13
	v_mul_f32_e64 v21, |v13|, s76
	v_add_f32_e32 v21, v21, v21
	v_exp_f32_e32 v21, v21
	s_nop 0
	v_add_f32_e32 v21, 1.0, v21
	v_rcp_f32_e32 v21, v21
	s_nop 0
	v_fma_f32 v21, v21, -2.0, 1.0
	v_mul_f32_e32 v22, 0x3d372713, v9
	v_mul_f32_e32 v22, v9, v22
	v_fma_f32 v22, v9, v22, v9
	v_mul_f32_e32 v22, 0x3f4c422a, v22
	v_mul_f32_e64 v23, |v22|, s76
	v_add_f32_e32 v23, v23, v23
	v_exp_f32_e32 v23, v23
	s_nop 0
	v_add_f32_e32 v23, 1.0, v23
	v_rcp_f32_e32 v23, v23
	s_nop 0
	v_fma_f32 v23, v23, -2.0, 1.0
	v_mul_f32_e32 v24, 0x3d372713, v5
	v_mul_f32_e32 v24, v5, v24
	v_fma_f32 v24, v5, v24, v5
	v_mul_f32_e32 v24, 0x3f4c422a, v24
	v_cmp_nlt_f32_e64 s[0:1], |v24|, s11
	s_and_saveexec_b64 s[2:3], s[0:1]
	s_xor_b64 s[0:1], exec, s[2:3]
	s_cbranch_execz .LBB0_995
	v_add_f32_e64 v25, |v24|, |v24|
	v_mul_f32_e32 v26, 0x3fb8aa3b, v25
	v_rndne_f32_e32 v27, v26
	v_sub_f32_e32 v28, v26, v27
	v_fma_f32 v26, v25, s76, -v26
	v_fmac_f32_e32 v26, 0x32a5705f, v25
	v_add_f32_e32 v26, v28, v26
	v_cvt_i32_f32_e32 v27, v27
	v_exp_f32_e32 v26, v26
	v_cmp_ngt_f32_e32 vcc, s71, v25
	v_ldexp_f32 v26, v26, v27
	s_nop 0
	v_cndmask_b32_e32 v26, 0, v26, vcc
	v_cmp_nlt_f32_e32 vcc, s30, v25
	s_nop 1
	v_cndmask_b32_e32 v25, v186, v26, vcc
	v_add_f32_e32 v25, 1.0, v25
	v_rcp_f32_e32 v25, v25
	s_nop 0
	v_fma_f32 v25, v25, -2.0, 1.0
